# SB quarters: single v_min(-z,126) via SGPR constant; diff row sums as scalar adds instead of v_pk_add
# speedup vs baseline: 1.0073x; 1.0073x over previous
; #define MFMA32(a, b, c) __builtin_amdgcn_mfma_f32_32x32x16_bf16((a), (b), (c), 0, 0, 0)
; #define VFRAG(ptr, off0, STR) ({ const s16x4 lo_ = vtr((ptr) + (off0)); const s16x4 hi_ = vtr((ptr) + (off0) + 8 * (STR)); (bf16x8){lo_[0], lo_[1], lo_[2], lo_[3], hi_[0], hi_[1], hi_[2], hi_[3]}; })
; __device__ __forceinline__ void diff_unit(const Frame& F, int b, int h, int qi, float lam, int dry) {
;     ...
;             float ps = 0.f;
; #pragma unroll
;             for (int r = 0; r < 16; ++r) { s0[r] = __builtin_amdgcn_exp2f(s0[r] * LOG2E - ms); ps += s0[r]; }
;             if (!meta) {
; #pragma unroll
;                 for (int r = 0; r < 16; ++r) { s1[r] = __builtin_amdgcn_exp2f(s1[r] * LOG2E - ms); ps += s1[r]; }
;             }
;             lsum += ps;
;             __builtin_amdgcn_s_setprio(1);
;             { const bf16x8 pf = pack_step(s0, 0);
;               O[0] = MFMA32(vpre0, pf, O[0]); O[1] = MFMA32(vpre1, pf, O[1]); O[2] = MFMA32(vpre2, pf, O[2]); O[3] = MFMA32(vpre3, pf, O[3]); }
;             if (!meta) {
;                 { const bf16x8 pf = pack_step(s0, 1);
;                   O[0] = MFMA32(vprf0, pf, O[0]); O[1] = MFMA32(vprf1, pf, O[1]);
; #pragma unroll
;                   for (int dt = 2; dt < 4; ++dt) { const bf16x8 vf = VFRAG(vb, 16 * DV_STR + 64 * dt, DV_STR); O[dt] = MFMA32(vf, pf, O[dt]); } }
; #pragma unroll
;                 for (int s2 = 0; s2 < 2; ++s2) { const bf16x8 pf = pack_step(s1, s2);
; #pragma unroll
;                     for (int dt = 0; dt < 4; ++dt) { const bf16x8 vf = VFRAG(vb, (32 + 16 * s2) * DV_STR + 64 * dt, DV_STR); O[dt] = MFMA32(vf, pf, O[dt]); } }
;             }
.LBB0_305:
	ds_read_b64_tr_b16 v[224:225], v222 offset:40064
	ds_read_b64_tr_b16 v[226:227], v222 offset:42624
	ds_read_b64_tr_b16 v[228:229], v222 offset:40128
	ds_read_b64_tr_b16 v[230:231], v222 offset:42688
	v_fma_f32 v80, v80, s88, -v185
	v_fma_f32 v81, v81, s88, -v185
	v_fma_f32 v82, v82, s88, -v185
	v_fma_f32 v83, v83, s88, -v185
	v_exp_f32_e32 v80, v80
	v_exp_f32_e32 v81, v81
	v_exp_f32_e32 v82, v82
	v_exp_f32_e32 v83, v83
	v_fma_f32 v84, v84, s88, -v185
	v_fma_f32 v85, v85, s88, -v185
	v_fma_f32 v86, v86, s88, -v185
	v_fma_f32 v87, v87, s88, -v185
	v_exp_f32_e32 v84, v84
	v_exp_f32_e32 v85, v85
	v_exp_f32_e32 v86, v86
	v_exp_f32_e32 v87, v87
	v_add_f32_e32 v236, v80, v82
	v_add_f32_e32 v237, v81, v83
	s_setprio 1
	v_cvt_pk_bf16_f32 v232, v80, v81
	v_cvt_pk_bf16_f32 v233, v82, v83
	v_cvt_pk_bf16_f32 v234, v84, v85
	v_cvt_pk_bf16_f32 v235, v86, v87
	v_add_f32_e32 v236, v236, v84
	v_add_f32_e32 v237, v237, v85
	v_add_f32_e32 v236, v236, v86
	v_add_f32_e32 v237, v237, v87
	v_mfma_f32_32x32x16_bf16 v[48:63], v[148:151], v[232:235], v[48:63]
	ds_read_b64_tr_b16 v[148:149], v222 offset:45056
	ds_read_b64_tr_b16 v[150:151], v222 offset:47616
	v_fma_f32 v88, v88, s88, -v185
	v_fma_f32 v89, v89, s88, -v185
	v_exp_f32_e32 v88, v88
	v_exp_f32_e32 v89, v89
	v_mfma_f32_32x32x16_bf16 v[32:47], v[144:147], v[232:235], v[32:47]
	ds_read_b64_tr_b16 v[144:145], v222 offset:45120
	ds_read_b64_tr_b16 v[146:147], v222 offset:47680
	v_fma_f32 v90, v90, s88, -v185
	v_fma_f32 v91, v91, s88, -v185
	v_exp_f32_e32 v90, v90
	v_exp_f32_e32 v91, v91
	v_add_f32_e32 v236, v236, v88
	v_add_f32_e32 v237, v237, v89
	v_cvt_pk_bf16_f32 v80, v88, v89
	v_mfma_f32_32x32x16_bf16 v[16:31], v[140:143], v[232:235], v[16:31]
	ds_read_b64_tr_b16 v[140:141], v222 offset:45184
	ds_read_b64_tr_b16 v[142:143], v222 offset:47744
	v_fma_f32 v92, v92, s88, -v185
	v_fma_f32 v93, v93, s88, -v185
	v_exp_f32_e32 v92, v92
	v_exp_f32_e32 v93, v93
	v_add_f32_e32 v236, v236, v90
	v_add_f32_e32 v237, v237, v91
	v_cvt_pk_bf16_f32 v81, v90, v91
	v_mfma_f32_32x32x16_bf16 v[0:15], v[136:139], v[232:235], v[0:15]
	ds_read_b64_tr_b16 v[136:137], v222 offset:45248
	ds_read_b64_tr_b16 v[138:139], v222 offset:47808
	v_fma_f32 v94, v94, s88, -v185
	v_fma_f32 v95, v95, s88, -v185
	v_exp_f32_e32 v94, v94
	v_exp_f32_e32 v95, v95
	v_add_f32_e32 v236, v236, v92
	v_add_f32_e32 v237, v237, v93
	v_cvt_pk_bf16_f32 v82, v92, v93
	v_cvt_pk_bf16_f32 v83, v94, v95
	v_add_f32_e32 v236, v236, v94
	v_add_f32_e32 v237, v237, v95
	s_nop 0
	v_mfma_f32_32x32x16_bf16 v[48:63], v[128:131], v[80:83], v[48:63]
	ds_read_b64_tr_b16 v[128:129], v222 offset:50176
	ds_read_b64_tr_b16 v[130:131], v222 offset:52736
	v_fma_f32 v64, v64, s88, -v185
	v_fma_f32 v65, v65, s88, -v185
	v_exp_f32_e32 v64, v64
	v_exp_f32_e32 v65, v65
	v_mfma_f32_32x32x16_bf16 v[32:47], v[132:135], v[80:83], v[32:47]
	ds_read_b64_tr_b16 v[132:133], v222 offset:50240
	ds_read_b64_tr_b16 v[134:135], v222 offset:52800
	v_fma_f32 v66, v66, s88, -v185
	v_fma_f32 v67, v67, s88, -v185
	v_exp_f32_e32 v66, v66
	v_exp_f32_e32 v67, v67
	v_add_f32_e32 v236, v236, v64
	v_add_f32_e32 v237, v237, v65
	v_cvt_pk_bf16_f32 v84, v64, v65
	s_waitcnt lgkmcnt(14)
	v_mfma_f32_32x32x16_bf16 v[16:31], v[224:227], v[80:83], v[16:31]
	ds_read_b64_tr_b16 v[224:225], v222 offset:50304
	ds_read_b64_tr_b16 v[226:227], v222 offset:52864
	v_fma_f32 v68, v68, s88, -v185
	v_fma_f32 v69, v69, s88, -v185
	v_exp_f32_e32 v68, v68
	v_exp_f32_e32 v69, v69
	v_add_f32_e32 v236, v236, v66
	v_add_f32_e32 v237, v237, v67
	v_cvt_pk_bf16_f32 v85, v66, v67
	s_waitcnt lgkmcnt(14)
	v_mfma_f32_32x32x16_bf16 v[0:15], v[228:231], v[80:83], v[0:15]
	ds_read_b64_tr_b16 v[228:229], v222 offset:50368
	ds_read_b64_tr_b16 v[230:231], v222 offset:52928
	v_fma_f32 v70, v70, s88, -v185
	v_fma_f32 v71, v71, s88, -v185
	v_exp_f32_e32 v70, v70
	v_exp_f32_e32 v71, v71
	v_add_f32_e32 v236, v236, v68
	v_add_f32_e32 v237, v237, v69
	v_cvt_pk_bf16_f32 v86, v68, v69
	v_cvt_pk_bf16_f32 v87, v70, v71
	v_add_f32_e32 v236, v236, v70
	v_add_f32_e32 v237, v237, v71
	s_nop 0
	s_waitcnt lgkmcnt(14)
	v_mfma_f32_32x32x16_bf16 v[48:63], v[148:151], v[84:87], v[48:63]
	v_fma_f32 v72, v72, s88, -v185
	v_fma_f32 v73, v73, s88, -v185
	v_exp_f32_e32 v72, v72
	v_exp_f32_e32 v73, v73
	s_waitcnt lgkmcnt(12)
	v_mfma_f32_32x32x16_bf16 v[32:47], v[144:147], v[84:87], v[32:47]
	v_fma_f32 v74, v74, s88, -v185
	v_fma_f32 v75, v75, s88, -v185
	v_exp_f32_e32 v74, v74
	v_exp_f32_e32 v75, v75
	v_add_f32_e32 v236, v236, v72
	v_add_f32_e32 v237, v237, v73
	v_cvt_pk_bf16_f32 v232, v72, v73
	s_waitcnt lgkmcnt(10)
	v_mfma_f32_32x32x16_bf16 v[16:31], v[140:143], v[84:87], v[16:31]
	v_fma_f32 v76, v76, s88, -v185
	v_fma_f32 v77, v77, s88, -v185
	v_exp_f32_e32 v76, v76
	v_exp_f32_e32 v77, v77
	v_add_f32_e32 v236, v236, v74
	v_add_f32_e32 v237, v237, v75
	v_cvt_pk_bf16_f32 v233, v74, v75
	s_waitcnt lgkmcnt(8)
	v_mfma_f32_32x32x16_bf16 v[0:15], v[136:139], v[84:87], v[0:15]
	v_fma_f32 v78, v78, s88, -v185
	v_fma_f32 v79, v79, s88, -v185
	v_exp_f32_e32 v78, v78
	v_exp_f32_e32 v79, v79
	v_add_f32_e32 v236, v236, v76
	v_add_f32_e32 v237, v237, v77
	v_cvt_pk_bf16_f32 v234, v76, v77
	v_cvt_pk_bf16_f32 v235, v78, v79
	v_add_f32_e32 v236, v236, v78
	v_add_f32_e32 v237, v237, v79
	v_add_f32_e32 v223, v236, v237
	v_add_f32_e32 v158, v158, v223
	s_waitcnt lgkmcnt(6)
	v_mfma_f32_32x32x16_bf16 v[48:63], v[128:131], v[232:235], v[48:63]
	s_waitcnt lgkmcnt(4)
	v_mfma_f32_32x32x16_bf16 v[32:47], v[132:135], v[232:235], v[32:47]
	s_waitcnt lgkmcnt(2)
	v_mfma_f32_32x32x16_bf16 v[16:31], v[224:227], v[232:235], v[16:31]
	s_waitcnt lgkmcnt(0)
	v_mfma_f32_32x32x16_bf16 v[0:15], v[228:231], v[232:235], v[0:15]
	s_setprio 0
	s_andn2_b64 vcc, exec, s[66:67]
	s_cbranch_vccnz .LBB0_296

; #define MFMA32(a, b, c) __builtin_amdgcn_mfma_f32_32x32x16_bf16((a), (b), (c), 0, 0, 0)
; #define VFRAG(ptr, off0, STR) ({ const s16x4 lo_ = vtr((ptr) + (off0)); const s16x4 hi_ = vtr((ptr) + (off0) + 8 * (STR)); (bf16x8){lo_[0], lo_[1], lo_[2], lo_[3], hi_[0], hi_[1], hi_[2], hi_[3]}; })
; __device__ __forceinline__ void diff_unit(const Frame& F, int b, int h, int qi, float lam, int dry) {
;     ...
;             float ps = 0.f;
; #pragma unroll
;             for (int r = 0; r < 16; ++r) { s0[r] = __builtin_amdgcn_exp2f(s0[r] * LOG2E - ms); ps += s0[r]; }
;             if (!meta) {
; #pragma unroll
;                 for (int r = 0; r < 16; ++r) { s1[r] = __builtin_amdgcn_exp2f(s1[r] * LOG2E - ms); ps += s1[r]; }
;             }
;             lsum += ps;
;             __builtin_amdgcn_s_setprio(1);
;             { const bf16x8 pf = pack_step(s0, 0);
;               O[0] = MFMA32(vpre0, pf, O[0]); O[1] = MFMA32(vpre1, pf, O[1]); O[2] = MFMA32(vpre2, pf, O[2]); O[3] = MFMA32(vpre3, pf, O[3]); }
;             if (!meta) {
;                 { const bf16x8 pf = pack_step(s0, 1);
;                   O[0] = MFMA32(vprf0, pf, O[0]); O[1] = MFMA32(vprf1, pf, O[1]);
; #pragma unroll
;                   for (int dt = 2; dt < 4; ++dt) { const bf16x8 vf = VFRAG(vb, 16 * DV_STR + 64 * dt, DV_STR); O[dt] = MFMA32(vf, pf, O[dt]); } }
; #pragma unroll
;                 for (int s2 = 0; s2 < 2; ++s2) { const bf16x8 pf = pack_step(s1, s2);
; #pragma unroll
;                     for (int dt = 0; dt < 4; ++dt) { const bf16x8 vf = VFRAG(vb, (32 + 16 * s2) * DV_STR + 64 * dt, DV_STR); O[dt] = MFMA32(vf, pf, O[dt]); } }
;             }
.LBB0_324:
	ds_read_b64_tr_b16 v[190:191], v188 offset:40064
	ds_read_b64_tr_b16 v[192:193], v188 offset:42624
	ds_read_b64_tr_b16 v[194:195], v188 offset:40128
	ds_read_b64_tr_b16 v[196:197], v188 offset:42688
	v_fma_f32 v80, v80, s88, -v158
	v_fma_f32 v81, v81, s88, -v158
	v_fma_f32 v82, v82, s88, -v158
	v_fma_f32 v83, v83, s88, -v158
	v_exp_f32_e32 v80, v80
	v_exp_f32_e32 v81, v81
	v_exp_f32_e32 v82, v82
	v_exp_f32_e32 v83, v83
	v_fma_f32 v84, v84, s88, -v158
	v_fma_f32 v85, v85, s88, -v158
	v_fma_f32 v86, v86, s88, -v158
	v_fma_f32 v87, v87, s88, -v158
	v_exp_f32_e32 v84, v84
	v_exp_f32_e32 v85, v85
	v_exp_f32_e32 v86, v86
	v_exp_f32_e32 v87, v87
	v_add_f32_e32 v202, v80, v82
	v_add_f32_e32 v203, v81, v83
	s_setprio 1
	v_cvt_pk_bf16_f32 v198, v80, v81
	v_cvt_pk_bf16_f32 v199, v82, v83
	v_cvt_pk_bf16_f32 v200, v84, v85
	v_cvt_pk_bf16_f32 v201, v86, v87
	v_add_f32_e32 v202, v202, v84
	v_add_f32_e32 v203, v203, v85
	v_add_f32_e32 v202, v202, v86
	v_add_f32_e32 v203, v203, v87
	v_mfma_f32_32x32x16_bf16 v[48:63], v[148:151], v[198:201], v[48:63]
	ds_read_b64_tr_b16 v[148:149], v188 offset:45056
	ds_read_b64_tr_b16 v[150:151], v188 offset:47616
	v_fma_f32 v88, v88, s88, -v158
	v_fma_f32 v89, v89, s88, -v158
	v_exp_f32_e32 v88, v88
	v_exp_f32_e32 v89, v89
	v_mfma_f32_32x32x16_bf16 v[32:47], v[144:147], v[198:201], v[32:47]
	ds_read_b64_tr_b16 v[144:145], v188 offset:45120
	ds_read_b64_tr_b16 v[146:147], v188 offset:47680
	v_fma_f32 v90, v90, s88, -v158
	v_fma_f32 v91, v91, s88, -v158
	v_exp_f32_e32 v90, v90
	v_exp_f32_e32 v91, v91
	v_add_f32_e32 v202, v202, v88
	v_add_f32_e32 v203, v203, v89
	v_cvt_pk_bf16_f32 v80, v88, v89
	v_mfma_f32_32x32x16_bf16 v[16:31], v[140:143], v[198:201], v[16:31]
	ds_read_b64_tr_b16 v[140:141], v188 offset:45184
	ds_read_b64_tr_b16 v[142:143], v188 offset:47744
	v_fma_f32 v92, v92, s88, -v158
	v_fma_f32 v93, v93, s88, -v158
	v_exp_f32_e32 v92, v92
	v_exp_f32_e32 v93, v93
	v_add_f32_e32 v202, v202, v90
	v_add_f32_e32 v203, v203, v91
	v_cvt_pk_bf16_f32 v81, v90, v91
	v_mfma_f32_32x32x16_bf16 v[0:15], v[136:139], v[198:201], v[0:15]
	ds_read_b64_tr_b16 v[136:137], v188 offset:45248
	ds_read_b64_tr_b16 v[138:139], v188 offset:47808
	v_fma_f32 v94, v94, s88, -v158
	v_fma_f32 v95, v95, s88, -v158
	v_exp_f32_e32 v94, v94
	v_exp_f32_e32 v95, v95
	v_add_f32_e32 v202, v202, v92
	v_add_f32_e32 v203, v203, v93
	v_cvt_pk_bf16_f32 v82, v92, v93
	v_cvt_pk_bf16_f32 v83, v94, v95
	v_add_f32_e32 v202, v202, v94
	v_add_f32_e32 v203, v203, v95
	s_nop 0
	v_mfma_f32_32x32x16_bf16 v[48:63], v[128:131], v[80:83], v[48:63]
	ds_read_b64_tr_b16 v[128:129], v188 offset:50176
	ds_read_b64_tr_b16 v[130:131], v188 offset:52736
	v_fma_f32 v64, v64, s88, -v158
	v_fma_f32 v65, v65, s88, -v158
	v_exp_f32_e32 v64, v64
	v_exp_f32_e32 v65, v65
	v_mfma_f32_32x32x16_bf16 v[32:47], v[132:135], v[80:83], v[32:47]
	ds_read_b64_tr_b16 v[132:133], v188 offset:50240
	ds_read_b64_tr_b16 v[134:135], v188 offset:52800
	v_fma_f32 v66, v66, s88, -v158
	v_fma_f32 v67, v67, s88, -v158
	v_exp_f32_e32 v66, v66
	v_exp_f32_e32 v67, v67
	v_add_f32_e32 v202, v202, v64
	v_add_f32_e32 v203, v203, v65
	v_cvt_pk_bf16_f32 v84, v64, v65
	s_waitcnt lgkmcnt(14)
	v_mfma_f32_32x32x16_bf16 v[16:31], v[190:193], v[80:83], v[16:31]
	ds_read_b64_tr_b16 v[190:191], v188 offset:50304
	ds_read_b64_tr_b16 v[192:193], v188 offset:52864
	v_fma_f32 v68, v68, s88, -v158
	v_fma_f32 v69, v69, s88, -v158
	v_exp_f32_e32 v68, v68
	v_exp_f32_e32 v69, v69
	v_add_f32_e32 v202, v202, v66
	v_add_f32_e32 v203, v203, v67
	v_cvt_pk_bf16_f32 v85, v66, v67
	s_waitcnt lgkmcnt(14)
	v_mfma_f32_32x32x16_bf16 v[0:15], v[194:197], v[80:83], v[0:15]
	ds_read_b64_tr_b16 v[194:195], v188 offset:50368
	ds_read_b64_tr_b16 v[196:197], v188 offset:52928
	v_fma_f32 v70, v70, s88, -v158
	v_fma_f32 v71, v71, s88, -v158
	v_exp_f32_e32 v70, v70
	v_exp_f32_e32 v71, v71
	v_add_f32_e32 v202, v202, v68
	v_add_f32_e32 v203, v203, v69
	v_cvt_pk_bf16_f32 v86, v68, v69
	v_cvt_pk_bf16_f32 v87, v70, v71
	v_add_f32_e32 v202, v202, v70
	v_add_f32_e32 v203, v203, v71
	s_nop 0
	s_waitcnt lgkmcnt(14)
	v_mfma_f32_32x32x16_bf16 v[48:63], v[148:151], v[84:87], v[48:63]
	v_fma_f32 v72, v72, s88, -v158
	v_fma_f32 v73, v73, s88, -v158
	v_exp_f32_e32 v72, v72
	v_exp_f32_e32 v73, v73
	s_waitcnt lgkmcnt(12)
	v_mfma_f32_32x32x16_bf16 v[32:47], v[144:147], v[84:87], v[32:47]
	v_fma_f32 v74, v74, s88, -v158
	v_fma_f32 v75, v75, s88, -v158
	v_exp_f32_e32 v74, v74
	v_exp_f32_e32 v75, v75
	v_add_f32_e32 v202, v202, v72
	v_add_f32_e32 v203, v203, v73
	v_cvt_pk_bf16_f32 v198, v72, v73
	s_waitcnt lgkmcnt(10)
	v_mfma_f32_32x32x16_bf16 v[16:31], v[140:143], v[84:87], v[16:31]
	v_fma_f32 v76, v76, s88, -v158
	v_fma_f32 v77, v77, s88, -v158
	v_exp_f32_e32 v76, v76
	v_exp_f32_e32 v77, v77
	v_add_f32_e32 v202, v202, v74
	v_add_f32_e32 v203, v203, v75
	v_cvt_pk_bf16_f32 v199, v74, v75
	s_waitcnt lgkmcnt(8)
	v_mfma_f32_32x32x16_bf16 v[0:15], v[136:139], v[84:87], v[0:15]
	v_fma_f32 v78, v78, s88, -v158
	v_fma_f32 v79, v79, s88, -v158
	v_exp_f32_e32 v78, v78
	v_exp_f32_e32 v79, v79
	v_add_f32_e32 v202, v202, v76
	v_add_f32_e32 v203, v203, v77
	v_cvt_pk_bf16_f32 v200, v76, v77
	v_cvt_pk_bf16_f32 v201, v78, v79
	v_add_f32_e32 v202, v202, v78
	v_add_f32_e32 v203, v203, v79
	v_add_f32_e32 v189, v202, v203
	v_add_f32_e32 v153, v153, v189
	s_waitcnt lgkmcnt(6)
	v_mfma_f32_32x32x16_bf16 v[48:63], v[128:131], v[198:201], v[48:63]
	s_waitcnt lgkmcnt(4)
	v_mfma_f32_32x32x16_bf16 v[32:47], v[132:135], v[198:201], v[32:47]
	s_waitcnt lgkmcnt(2)
	v_mfma_f32_32x32x16_bf16 v[16:31], v[190:193], v[198:201], v[16:31]
	s_waitcnt lgkmcnt(0)
	v_mfma_f32_32x32x16_bf16 v[0:15], v[194:197], v[198:201], v[0:15]
	s_setprio 0
	s_andn2_b64 vcc, exec, s[90:91]
	s_cbranch_vccnz .LBB0_315

; #define LAS __attribute__((address_space(3)))
; #define S_LOAD(key0) do { st0 = *(const u32x4*)(kg + (size_t)(key0) * 1024); st1 = *(const u32x4*)(kg + (size_t)((key0) + 64) * 1024); st2 = *(const u32x4*)(vg + (size_t)(key0) * 1024); st3 = *(const u32x4*)(vg + (size_t)((key0) + 64) * 1024); } while (0)
; #define S_STORE(buf) do { *(LAS u32x4*)(lds + klds + (buf) * SK_BUF) = st0; *(LAS u32x4*)(lds + klds + (buf) * SK_BUF + 64 * SK_STR) = st1; \
;         *(LAS u32x4*)(lds + vlds + (buf) * SV_BUF) = st2; *(LAS u32x4*)(lds + vlds + (buf) * SV_BUF + 64 * SV_STR) = st3; } while (0)
; __device__ __forceinline__ void sb_unit(const Frame& F, int b, int hd, int qi, int dry) {
;     LAS unsigned char* lds = F.lds;
;     const int tid = F.tid, lane = F.lane, wid = F.wave, r32 = lane & 31, hi = lane >> 5;
;     const size_t rowbase = (size_t)b * LT;
;     const int tq0 = NMETA + 256 * qi, tqw = tq0 + 32 * wid, tq = tqw + r32;
;     bf16* QB = (bf16*)(F.ws + WS_SEC) + 3 * SEC_ELEMS; const bf16* KB = QB + SEC_ELEMS; const bf16* VB = QB + 2 * SEC_ELEMS;
;     bf16x8 qf[4];
;     { const bf16* qp = QB + (rowbase + tq) * 1024 + 64 * hd + 8 * hi;
; #pragma unroll
;       for (int ks = 0; ks < 4; ++ks) qf[ks] = *(const bf16x8*)(qp + 16 * ks); }
;     const int srow = tid >> 3, sc16 = tid & 7;
;     const bf16* kg = KB + (rowbase + srow) * 1024 + 64 * hd + sc16 * 8;
;     const bf16* vg = VB + (rowbase + srow) * 1024 + 64 * hd + sc16 * 8;
;     const int klds = S_KOFF + srow * SK_STR + sc16 * 16, vlds = S_VOFF + srow * SV_STR + sc16 * 16;
;     u32x4 st0, st1, st2, st3;
;     ...
;     const int jmax = 2 * qi + 1, nt = jmax + 2;
;     __syncthreads();
;     S_LOAD(NMETA + 128 * jmax); S_STORE(0);
;     __syncthreads();
;     f32x16 O[2];
; #pragma unroll
;     for (int dt = 0; dt < 2; ++dt)
; #pragma unroll
;         for (int r = 0; r < 16; ++r) O[dt][r] = 0.f;
;     float C = 0.f;
;     bool dead = false;
;     constexpr float SB_DEAD = -150.0f;
;     LAS int* flags = (LAS int*)(lds + S_VOFF + 2 * SV_BUF);
;     const int kra = S_KOFF + r32 * SK_STR + hi * 16;
;     const int vra = S_VOFF + (4 * hi + ((lane & 15) >> 2)) * SV_STR + (16 * ((lane >> 4) & 1) + 4 * (lane & 3)) * 2;
.LBB0_330:
	s_mov_b32 s60, 0x42fc0000
	v_readlane_b32 s85, v254, 55
	v_readlane_b32 s80, v254, 57
	s_lshl_b32 s20, s85, 5
	v_readlane_b32 s82, v254, 59
	v_readlane_b32 s83, v254, 60
	s_add_u32 s6, s82, 0xef00000
	s_addc_u32 s7, s83, 0
	s_add_u32 s8, s82, 0x13000000
	s_addc_u32 s9, s83, 0
	s_add_u32 s12, s82, 0x17100000
	s_addc_u32 s13, s83, 0
	v_lshrrev_b32_e32 v96, 3, v177
	v_and_b32_e32 v1, 7, v177
	s_lshl_b32 s1, s85, 2
	s_add_i32 s10, 0, 0x15000
	v_mul_u32_u24_e32 v2, 0x90, v96
	v_lshlrev_b32_e32 v3, 4, v1
	s_add_i32 s21, s10, s1
	s_mul_i32 s1, s85, 0x1200
	s_waitcnt vmcnt(2)
	v_add3_u32 v116, 0, v2, v3
	v_mul_u32_u24_e32 v2, 0x90, v204
	s_add_i32 s1, s1, 0
	v_lshlrev_b32_e32 v0, 3, v1
	s_movk_i32 s0, 0x90
	v_mul_u32_u24_e32 v4, 0xc0, v207
	v_add3_u32 v118, 0, v2, v156
	s_waitcnt vmcnt(1)
	v_lshl_add_u32 v120, v1, 2, s10
	v_mov_b32_e32 v1, s1
	v_add_u32_e32 v2, s1, v3
	v_lshrrev_b32_e32 v3, 3, v176
	v_mov_b32_e32 v99, 0
	v_add3_u32 v119, 0, v4, v208
	v_mad_u32_u24 v1, v204, s0, v1
	v_mul_u32_u24_e32 v4, 0x90, v3
	v_lshlrev_b32_e32 v100, 11, v3
	v_readlane_b32 s77, v254, 62
	v_readlane_b32 s78, v254, 45
	v_readlane_b32 s86, v254, 43
	v_readlane_b32 s81, v254, 58
	v_mov_b32_e32 v97, v99
	s_mov_b32 s15, 0
	v_mad_u32_u24 v117, v96, 48, v116
	v_cmp_gt_u32_e64 s[2:3], 32, v176
	v_cmp_eq_u32_e64 s[4:5], 0, v176
	v_mov_b32_e32 v101, v99
	v_or_b32_e32 v102, 0x4000, v100
	v_mov_b32_e32 v103, v99
	v_or_b32_e32 v104, 0x8000, v100
	v_mov_b32_e32 v105, v99
	v_or_b32_e32 v106, 0xc000, v100
	v_mov_b32_e32 v107, v99
	v_mov_b32_e32 v121, 0x1010
	v_mov_b32_e32 v108, v152
	v_mov_b32_e32 v109, v99
	v_lshlrev_b32_e32 v98, 1, v0
	s_mov_b32 s22, 0xc3160000
	v_add_u32_e32 v122, v1, v154
	v_add_u32_e32 v123, v2, v4
	s_mov_b32 s23, s77
	s_mov_b32 s24, s77
	v_readlane_b32 s79, v254, 46
	v_readlane_b32 s87, v254, 44
	v_readlane_b32 s88, v254, 42
	v_readlane_b32 s89, v254, 41
	v_readlane_b32 s91, v254, 40
	s_branch .LBB0_332

; #define LAS __attribute__((address_space(3)))
; #define S_LOAD(key0) do { st0 = *(const u32x4*)(kg + (size_t)(key0) * 1024); st1 = *(const u32x4*)(kg + (size_t)((key0) + 64) * 1024); st2 = *(const u32x4*)(vg + (size_t)(key0) * 1024); st3 = *(const u32x4*)(vg + (size_t)((key0) + 64) * 1024); } while (0)
; __device__ __forceinline__ void sb_unit(const Frame& F, int b, int hd, int qi, int dry) {
;     ...
;         const int key0 = meta ? 0 : NMETA + 128 * (jmax - it);
;         if (it + 1 < nt) { const int nk = (it + 1 > jmax) ? 0 : NMETA + 128 * (jmax - it - 1); S_LOAD(nk); }
;         if (!dead && (meta || key0 < tqw + 31)) {
;             const LAS unsigned char* kb = lds + kra + (it & 1) * SK_BUF;
;             const LAS unsigned char* vb = lds + vra + (it & 1) * SV_BUF;
;     ...
;             float run = C;
;             if (!meta && key0 + 96 < tqw + 31) SB_HALF(96);
.LBB0_337:
	s_xor_b64 s[0:1], s[0:1], -1
	s_andn2_b64 vcc, exec, s[0:1]
	s_mov_b64 s[0:1], -1
	s_cbranch_vccnz .LBB0_350
	s_add_i32 s35, s33, 0xffffff10
	s_cmp_gt_u32 s36, s29
	s_cselect_b64 s[18:19], -1, 0
	s_and_b64 s[0:1], s[18:19], exec
	s_cselect_b32 s35, 0, s35
	s_cmp_lt_i32 s35, s30
	s_cselect_b64 s[0:1], -1, 0
	s_or_b64 s[0:1], s[18:19], s[0:1]
	s_andn2_b64 vcc, exec, s[0:1]
	s_mov_b64 s[0:1], 0
	s_cbranch_vccnz .LBB0_350
	s_and_b32 s0, s36, 1
	s_mul_i32 s36, s0, 0x4800
	s_mul_i32 s37, s0, 0x6000
	s_or_b32 s0, s35, 0x41
	s_cmp_ge_i32 s0, s26
	s_cselect_b64 s[0:1], -1, 0
	s_or_b64 s[0:1], s[18:19], s[0:1]
	s_and_b64 vcc, exec, s[0:1]
	v_add_u32_e32 v129, s36, v118
	v_or_b32_e32 v127, s35, v205
	v_add_u32_e32 v128, s37, v119
	s_cbranch_vccnz .LBB0_341
	ds_read_b128 v[32:35], v129 offset:13824
	ds_read_b128 v[80:83], v129 offset:13856
	v_exp_f32_e32 v135, v125
	v_sub_u32_e32 v134, v115, v127
	v_cmp_lt_i32_e32 vcc, 0, v134
	s_waitcnt lgkmcnt(1)
	v_mfma_f32_32x32x16_bf16 v[32:47], v[32:35], v[48:51], 0
	v_cmp_lt_i32_e64 s[0:1], 27, v134
	s_waitcnt lgkmcnt(0)
	v_mfma_f32_32x32x16_bf16 v[32:47], v[80:83], v[52:55], v[32:47]
	ds_read_b128 v[80:83], v129 offset:13888
	ds_read_b128 v[130:133], v129 offset:13920
	s_waitcnt lgkmcnt(1)
	v_mfma_f32_32x32x16_bf16 v[32:47], v[80:83], v[56:59], v[32:47]
	ds_read_b64_tr_b16 v[92:93], v128 offset:55296
	ds_read_b64_tr_b16 v[94:95], v128 offset:56832
	ds_read_b64_tr_b16 v[90:91], v128 offset:56896
	ds_read_b64_tr_b16 v[88:89], v128 offset:55360
	ds_read_b64_tr_b16 v[84:85], v128 offset:58368
	ds_read_b64_tr_b16 v[86:87], v128 offset:59904
	ds_read_b64_tr_b16 v[82:83], v128 offset:59968
	ds_read_b64_tr_b16 v[80:81], v128 offset:58432
	s_waitcnt lgkmcnt(8)
	v_mfma_f32_32x32x16_bf16 v[32:47], v[130:133], v[60:63], v[32:47]
	s_nop 11
	v_min_f32_e64 v32, -v32, s60
	v_min_f32_e64 v33, -v33, s60
	v_exp_f32_e32 v32, v32
	v_min_f32_e64 v34, -v34, s60
	v_exp_f32_e32 v33, v33
	v_exp_f32_e32 v34, v34
	v_min_f32_e64 v35, -v35, s60
	v_exp_f32_e32 v130, v35
	v_add_f32_e32 v35, 1.0, v32
	v_add_f32_e32 v131, 1.0, v33
	v_rcp_f32_e32 v35, v35
	v_add_f32_e32 v132, 1.0, v34
	v_rcp_f32_e32 v131, v131
	v_min_f32_e64 v36, -v36, s60
	v_rcp_f32_e32 v132, v132
	v_exp_f32_e32 v36, v36
	v_add_f32_e32 v133, 1.0, v130
	v_rcp_f32_e32 v136, v133
	v_mul_f32_e32 v32, v32, v35
	v_mul_f32_e32 v133, v135, v35
	v_mul_f32_e32 v33, v33, v131
	v_mul_f32_e32 v137, v135, v131
	v_cndmask_b32_e32 v35, 1.0, v32, vcc
	v_cndmask_b32_e32 v138, 0, v133, vcc
	v_cmp_lt_i32_e32 vcc, 1, v134
	v_mul_f32_e32 v34, v34, v132
	v_mul_f32_e32 v32, v135, v132
	v_cndmask_b32_e32 v131, 1.0, v33, vcc
	v_cndmask_b32_e32 v137, 0, v137, vcc
	v_cmp_lt_i32_e32 vcc, 2, v134
	v_min_f32_e64 v39, -v39, s60
	v_cndmask_b32_e32 v33, 1.0, v34, vcc
	v_add_f32_e32 v34, 1.0, v36
	v_rcp_f32_e32 v34, v34
	v_cndmask_b32_e32 v139, 0, v32, vcc
	v_mul_f32_e32 v32, v130, v136
	v_cmp_lt_i32_e32 vcc, 3, v134
	v_exp_f32_e32 v39, v39
	v_cndmask_b32_e32 v133, 1.0, v32, vcc
	v_mul_f32_e32 v32, v135, v136
	v_cndmask_b32_e32 v136, 0, v32, vcc
	v_mul_f32_e32 v32, v36, v34
	v_min_f32_e64 v36, -v37, s60
	v_exp_f32_e32 v36, v36
	v_cmp_lt_i32_e32 vcc, 8, v134
	v_mul_f32_e32 v34, v135, v34
	v_cndmask_b32_e32 v140, 0, v34, vcc
	v_add_f32_e32 v34, 1.0, v36
	v_rcp_f32_e32 v34, v34
	v_min_f32_e64 v37, -v38, s60
	v_exp_f32_e32 v37, v37
	v_cndmask_b32_e32 v32, 1.0, v32, vcc
	v_mul_f32_e32 v36, v36, v34
	v_cmp_lt_i32_e32 vcc, 9, v134
	v_mul_f32_e32 v34, v135, v34
	v_min_f32_e64 v42, -v42, s60
	v_cndmask_b32_e32 v38, 1.0, v36, vcc
	v_add_f32_e32 v36, 1.0, v37
	v_rcp_f32_e32 v36, v36
	v_cndmask_b32_e32 v141, 0, v34, vcc
	v_cmp_lt_i32_e32 vcc, 10, v134
	v_exp_f32_e32 v42, v42
	v_mul_f32_e32 v34, v37, v36
	v_add_f32_e32 v37, 1.0, v39
	v_rcp_f32_e32 v37, v37
	v_cndmask_b32_e32 v142, 1.0, v34, vcc
	v_mul_f32_e32 v34, v135, v36
	v_cndmask_b32_e32 v143, 0, v34, vcc
	v_mul_f32_e32 v34, v39, v37
	v_cmp_lt_i32_e32 vcc, 11, v134
	v_min_f32_e64 v36, -v40, s60
	v_exp_f32_e32 v36, v36
	v_cndmask_b32_e32 v39, 1.0, v34, vcc
	v_mul_f32_e32 v34, v135, v37
	v_min_f32_e64 v37, -v41, s60
	v_exp_f32_e32 v37, v37
	v_cndmask_b32_e32 v40, 0, v34, vcc
	v_add_f32_e32 v34, 1.0, v36
	v_rcp_f32_e32 v34, v34
	v_add_f32_e32 v41, 1.0, v37
	v_rcp_f32_e32 v41, v41
	v_cmp_lt_i32_e32 vcc, 16, v134
	v_mul_f32_e32 v36, v36, v34
	v_mul_f32_e32 v34, v135, v34
	v_cndmask_b32_e32 v144, 0, v34, vcc
	v_mul_f32_e32 v34, v37, v41
	v_add_f32_e32 v37, 1.0, v42
	v_rcp_f32_e32 v37, v37
	v_cndmask_b32_e32 v36, 1.0, v36, vcc
	v_cmp_lt_i32_e32 vcc, 17, v134
	v_min_f32_e64 v45, -v45, s60
	v_cndmask_b32_e32 v145, 1.0, v34, vcc
	v_mul_f32_e32 v34, v135, v41
	v_cndmask_b32_e32 v41, 0, v34, vcc
	v_mul_f32_e32 v34, v42, v37
	v_cmp_lt_i32_e32 vcc, 18, v134
	v_min_f32_e64 v42, -v43, s60
	v_exp_f32_e32 v42, v42
	v_cndmask_b32_e32 v43, 1.0, v34, vcc
	v_mul_f32_e32 v34, v135, v37
	v_min_f32_e64 v37, -v44, s60
	v_exp_f32_e32 v37, v37
	v_cndmask_b32_e32 v146, 0, v34, vcc
	v_add_f32_e32 v34, 1.0, v42
	v_rcp_f32_e32 v34, v34
	v_add_f32_e32 v44, 1.0, v37
	v_rcp_f32_e32 v44, v44
	v_exp_f32_e32 v45, v45
	v_min_f32_e64 v46, -v46, s60
	v_min_f32_e64 v47, -v47, s60
	v_exp_f32_e32 v46, v46
	v_exp_f32_e32 v47, v47
	v_mul_f32_e32 v42, v42, v34
	v_cmp_lt_i32_e32 vcc, 19, v134
	v_mul_f32_e32 v34, v135, v34
	v_add_f32_e32 v130, 1.0, v46
	v_cndmask_b32_e32 v147, 0, v34, vcc
	v_mul_f32_e32 v34, v37, v44
	v_add_f32_e32 v37, 1.0, v45
	v_rcp_f32_e32 v37, v37
	v_add_f32_e32 v132, 1.0, v47
	v_rcp_f32_e32 v130, v130
	v_rcp_f32_e32 v132, v132
	v_cndmask_b32_e32 v42, 1.0, v42, vcc
	v_cmp_lt_i32_e32 vcc, 24, v134
	v_mul_f32_e32 v44, v135, v44
	v_mul_f32_e32 v45, v45, v37
	v_cndmask_b32_e32 v34, 1.0, v34, vcc
	v_cndmask_b32_e32 v44, 0, v44, vcc
	v_cmp_lt_i32_e32 vcc, 25, v134
	v_mul_f32_e32 v37, v135, v37
	v_mul_f32_e32 v46, v46, v130
	v_cndmask_b32_e32 v45, 1.0, v45, vcc
	v_cndmask_b32_e32 v37, 0, v37, vcc
	v_cmp_lt_i32_e32 vcc, 26, v134
	v_mul_f32_e32 v47, v47, v132
	v_cndmask_b32_e64 v47, 1.0, v47, s[0:1]
	v_cndmask_b32_e32 v46, 1.0, v46, vcc
	v_mul_f32_e32 v34, v34, v45
	v_mul_f32_e32 v134, v46, v47
	v_mul_f32_e32 v134, v34, v134
	v_mov_b32_e32 v148, v134
	v_mov_b32_e32 v240, v134
	s_nop 1
	v_permlane32_swap_b32_e32 v148, v240
	v_cndmask_b32_e64 v148, v148, v240, s[2:3]
	v_mul_f32_e32 v34, v135, v130
	v_cndmask_b32_e32 v149, 0, v34, vcc
	v_mul_f32_e32 v34, v135, v132
	v_cndmask_b32_e64 v34, 0, v34, s[0:1]
	s_waitcnt lgkmcnt(0)
; __device__ __forceinline__ void sb_unit(const Frame& F, int b, int hd, int qi, int dry) {
;     ...
;             float run = C;
;             if (!meta && key0 + 96 < tqw + 31) SB_HALF(96);
;             if (!meta && key0 + 64 < tqw + 31 && __any(run >= SB_DEAD)) SB_HALF(64);
	v_cndmask_b32_e64 v130, 1.0, v148, s[2:3]
	v_mul_f32_e32 v135, v34, v130
	v_mul_f32_e32 v34, v36, v145
	v_mul_f32_e32 v36, v43, v42
	v_mul_f32_e32 v36, v34, v36
	v_mul_f32_e32 v32, v32, v38
	v_mul_f32_e32 v34, v142, v39
	v_mov_b32_e32 v150, v36
	v_mov_b32_e32 v240, v36
	s_nop 1
	v_permlane32_swap_b32_e32 v150, v240
	v_cndmask_b32_e64 v150, v150, v240, s[2:3]
	v_mul_f32_e32 v34, v32, v34
	v_mul_f32_e32 v47, v47, v130
	v_mov_b32_e32 v130, v34
	v_mov_b32_e32 v240, v34
	s_nop 1
	v_permlane32_swap_b32_e32 v130, v240
	v_cndmask_b32_e64 v130, v130, v240, s[2:3]
	v_mul_f32_e32 v46, v46, v47
	v_mul_f32_e32 v32, v134, v148
	s_waitcnt lgkmcnt(1)
	v_mul_f32_e32 v132, v36, v150
	v_mul_f32_e32 v45, v45, v46
	v_mul_f32_e32 v46, v37, v46
	s_waitcnt lgkmcnt(0)
	v_cndmask_b32_e64 v134, 1.0, v130, s[2:3]
	v_pk_mul_f32 v[36:37], v[32:33], v[132:133]
	v_pk_mul_f32 v[34:35], v[34:35], v[130:131]
	v_mul_f32_e32 v132, v36, v134
	v_mul_f32_e32 v134, v39, v132
	v_mul_f32_e32 v142, v142, v134
	v_mul_f32_e32 v148, v38, v142
	v_pk_mul_f32 v[38:39], v[34:35], v[36:37]
	v_mov_b32_e32 v130, v39
	v_mov_b32_e32 v240, v39
	s_nop 1
	v_permlane32_swap_b32_e32 v130, v240
	v_cndmask_b32_e64 v130, v130, v240, s[2:3]
	v_mul_f32_e32 v37, v40, v132
	v_mul_f32_e32 v40, v143, v134
	v_mul_f32_e32 v36, v141, v142
	v_mul_f32_e32 v132, v140, v148
	s_waitcnt lgkmcnt(0)
	v_cndmask_b32_e64 v34, 1.0, v130, s[2:3]
	v_mul_f32_e32 v34, v38, v34
	v_mul_f32_e32 v35, v133, v34
	v_mul_f32_e32 v33, v33, v35
	v_mul_f32_e32 v131, v131, v33
	v_mul_f32_e32 v133, v136, v34
	v_mul_f32_e32 v35, v139, v35
	v_mul_f32_e32 v33, v137, v33
	v_mul_f32_e32 v34, v138, v131
	v_cvt_pk_bf16_f32 v34, v34, v33
	v_cvt_pk_bf16_f32 v35, v35, v133
	v_cvt_pk_bf16_f32 v36, v132, v36
	v_cvt_pk_bf16_f32 v37, v40, v37
	v_cndmask_b32_e64 v33, 1.0, v150, s[2:3]
	v_mul_f32_e32 v32, v32, v33
	v_mfma_f32_32x32x16_bf16 v[16:31], v[92:95], v[34:37], v[16:31]
	v_mul_f32_e32 v33, v42, v32
	v_mul_f32_e32 v42, v43, v33
	v_mul_f32_e32 v43, v145, v42
	v_mul_f32_e32 v47, v149, v47
	v_mul_f32_e32 v40, v44, v45
	v_mul_f32_e32 v44, v147, v32
	v_mul_f32_e32 v33, v146, v33
	v_mfma_f32_32x32x16_bf16 v[0:15], v[88:91], v[34:37], v[0:15]
	v_mul_f32_e32 v32, v41, v42
	v_mul_f32_e32 v34, v144, v43
	v_cvt_pk_bf16_f32 v32, v34, v32
	v_cvt_pk_bf16_f32 v33, v33, v44
	v_cvt_pk_bf16_f32 v34, v40, v46
	v_cvt_pk_bf16_f32 v35, v47, v135
	v_mul_f32_e32 v36, v39, v130
	v_mul_f32_e32 v36, v38, v36
	v_mfma_f32_32x32x16_bf16 v[16:31], v[84:87], v[32:35], v[16:31]
	v_log_f32_e32 v36, v36
	s_nop 0
	v_add_f32_e32 v125, v125, v36
	v_mfma_f32_32x32x16_bf16 v[0:15], v[80:83], v[32:35], v[0:15]
.LBB0_341:
	s_or_b32 s0, s35, 33
	s_cmp_ge_i32 s0, s26
	s_cselect_b64 s[0:1], -1, 0
	s_or_b64 s[0:1], s[18:19], s[0:1]
	s_and_b64 vcc, exec, s[0:1]
	s_cbranch_vccnz .LBB0_344
	v_cmp_le_f32_e32 vcc, s22, v125
	s_cbranch_vccz .LBB0_344
	ds_read_b128 v[32:35], v129 offset:9216
	ds_read_b128 v[80:83], v129 offset:9248
	v_exp_f32_e32 v135, v125
	v_sub_u32_e32 v134, v124, v127
	v_cmp_lt_i32_e32 vcc, 0, v134
	s_waitcnt lgkmcnt(1)
	v_mfma_f32_32x32x16_bf16 v[32:47], v[32:35], v[48:51], 0
	v_cmp_lt_i32_e64 s[0:1], 27, v134
	s_waitcnt lgkmcnt(0)
	v_mfma_f32_32x32x16_bf16 v[32:47], v[80:83], v[52:55], v[32:47]
	ds_read_b128 v[80:83], v129 offset:9280
	ds_read_b128 v[130:133], v129 offset:9312
	s_waitcnt lgkmcnt(1)
	v_mfma_f32_32x32x16_bf16 v[32:47], v[80:83], v[56:59], v[32:47]
	ds_read_b64_tr_b16 v[92:93], v128 offset:49152
	ds_read_b64_tr_b16 v[94:95], v128 offset:50688
	ds_read_b64_tr_b16 v[90:91], v128 offset:50752
	ds_read_b64_tr_b16 v[88:89], v128 offset:49216
	ds_read_b64_tr_b16 v[84:85], v128 offset:52224
	ds_read_b64_tr_b16 v[86:87], v128 offset:53760
	ds_read_b64_tr_b16 v[82:83], v128 offset:53824
	ds_read_b64_tr_b16 v[80:81], v128 offset:52288
	s_waitcnt lgkmcnt(8)
	v_mfma_f32_32x32x16_bf16 v[32:47], v[130:133], v[60:63], v[32:47]
	s_nop 11
	v_min_f32_e64 v32, -v32, s60
	v_min_f32_e64 v33, -v33, s60
	v_exp_f32_e32 v32, v32
	v_min_f32_e64 v34, -v34, s60
	v_exp_f32_e32 v33, v33
	v_exp_f32_e32 v34, v34
	v_min_f32_e64 v35, -v35, s60
	v_exp_f32_e32 v130, v35
	v_add_f32_e32 v35, 1.0, v32
	v_add_f32_e32 v131, 1.0, v33
	v_rcp_f32_e32 v35, v35
	v_add_f32_e32 v132, 1.0, v34
	v_rcp_f32_e32 v131, v131
	v_min_f32_e64 v36, -v36, s60
	v_rcp_f32_e32 v132, v132
	v_exp_f32_e32 v36, v36
	v_add_f32_e32 v133, 1.0, v130
	v_rcp_f32_e32 v136, v133
	v_mul_f32_e32 v32, v32, v35
	v_mul_f32_e32 v133, v135, v35
	v_mul_f32_e32 v33, v33, v131
	v_mul_f32_e32 v137, v135, v131
	v_cndmask_b32_e32 v35, 1.0, v32, vcc
	v_cndmask_b32_e32 v138, 0, v133, vcc
	v_cmp_lt_i32_e32 vcc, 1, v134
	v_mul_f32_e32 v34, v34, v132
	v_mul_f32_e32 v32, v135, v132
	v_cndmask_b32_e32 v131, 1.0, v33, vcc
	v_cndmask_b32_e32 v137, 0, v137, vcc
	v_cmp_lt_i32_e32 vcc, 2, v134
	v_min_f32_e64 v39, -v39, s60
	v_cndmask_b32_e32 v33, 1.0, v34, vcc
	v_add_f32_e32 v34, 1.0, v36
	v_rcp_f32_e32 v34, v34
	v_cndmask_b32_e32 v139, 0, v32, vcc
	v_mul_f32_e32 v32, v130, v136
	v_cmp_lt_i32_e32 vcc, 3, v134
	v_exp_f32_e32 v39, v39
	v_cndmask_b32_e32 v133, 1.0, v32, vcc
	v_mul_f32_e32 v32, v135, v136
	v_cndmask_b32_e32 v136, 0, v32, vcc
	v_mul_f32_e32 v32, v36, v34
	v_min_f32_e64 v36, -v37, s60
	v_exp_f32_e32 v36, v36
	v_cmp_lt_i32_e32 vcc, 8, v134
	v_mul_f32_e32 v34, v135, v34
	v_cndmask_b32_e32 v140, 0, v34, vcc
	v_add_f32_e32 v34, 1.0, v36
	v_rcp_f32_e32 v34, v34
	v_min_f32_e64 v37, -v38, s60
	v_exp_f32_e32 v37, v37
	v_cndmask_b32_e32 v32, 1.0, v32, vcc
	v_mul_f32_e32 v36, v36, v34
	v_cmp_lt_i32_e32 vcc, 9, v134
	v_mul_f32_e32 v34, v135, v34
	v_min_f32_e64 v42, -v42, s60
	v_cndmask_b32_e32 v38, 1.0, v36, vcc
	v_add_f32_e32 v36, 1.0, v37
	v_rcp_f32_e32 v36, v36
; __device__ __forceinline__ void sb_unit(const Frame& F, int b, int hd, int qi, int dry) {
;     ...
;             float run = C;
;             if (!meta && key0 + 96 < tqw + 31) SB_HALF(96);
;             if (!meta && key0 + 64 < tqw + 31 && __any(run >= SB_DEAD)) SB_HALF(64);
	v_cndmask_b32_e32 v141, 0, v34, vcc
	v_cmp_lt_i32_e32 vcc, 10, v134
	v_exp_f32_e32 v42, v42
	v_mul_f32_e32 v34, v37, v36
	v_add_f32_e32 v37, 1.0, v39
	v_rcp_f32_e32 v37, v37
	v_cndmask_b32_e32 v142, 1.0, v34, vcc
	v_mul_f32_e32 v34, v135, v36
	v_cndmask_b32_e32 v143, 0, v34, vcc
	v_mul_f32_e32 v34, v39, v37
	v_cmp_lt_i32_e32 vcc, 11, v134
	v_min_f32_e64 v36, -v40, s60
	v_exp_f32_e32 v36, v36
	v_cndmask_b32_e32 v39, 1.0, v34, vcc
	v_mul_f32_e32 v34, v135, v37
	v_min_f32_e64 v37, -v41, s60
	v_exp_f32_e32 v37, v37
	v_cndmask_b32_e32 v40, 0, v34, vcc
	v_add_f32_e32 v34, 1.0, v36
	v_rcp_f32_e32 v34, v34
	v_add_f32_e32 v41, 1.0, v37
	v_rcp_f32_e32 v41, v41
	v_cmp_lt_i32_e32 vcc, 16, v134
	v_mul_f32_e32 v36, v36, v34
	v_mul_f32_e32 v34, v135, v34
	v_cndmask_b32_e32 v144, 0, v34, vcc
	v_mul_f32_e32 v34, v37, v41
	v_add_f32_e32 v37, 1.0, v42
	v_rcp_f32_e32 v37, v37
	v_cndmask_b32_e32 v36, 1.0, v36, vcc
	v_cmp_lt_i32_e32 vcc, 17, v134
	v_min_f32_e64 v45, -v45, s60
	v_cndmask_b32_e32 v145, 1.0, v34, vcc
	v_mul_f32_e32 v34, v135, v41
	v_cndmask_b32_e32 v41, 0, v34, vcc
	v_mul_f32_e32 v34, v42, v37
	v_cmp_lt_i32_e32 vcc, 18, v134
	v_min_f32_e64 v42, -v43, s60
	v_exp_f32_e32 v42, v42
	v_cndmask_b32_e32 v43, 1.0, v34, vcc
	v_mul_f32_e32 v34, v135, v37
	v_min_f32_e64 v37, -v44, s60
	v_exp_f32_e32 v37, v37
	v_cndmask_b32_e32 v146, 0, v34, vcc
	v_add_f32_e32 v34, 1.0, v42
	v_rcp_f32_e32 v34, v34
	v_add_f32_e32 v44, 1.0, v37
	v_rcp_f32_e32 v44, v44
	v_exp_f32_e32 v45, v45
	v_min_f32_e64 v46, -v46, s60
	v_min_f32_e64 v47, -v47, s60
	v_exp_f32_e32 v46, v46
	v_exp_f32_e32 v47, v47
	v_mul_f32_e32 v42, v42, v34
	v_cmp_lt_i32_e32 vcc, 19, v134
	v_mul_f32_e32 v34, v135, v34
	v_add_f32_e32 v130, 1.0, v46
	v_cndmask_b32_e32 v147, 0, v34, vcc
	v_mul_f32_e32 v34, v37, v44
	v_add_f32_e32 v37, 1.0, v45
	v_rcp_f32_e32 v37, v37
	v_add_f32_e32 v132, 1.0, v47
	v_rcp_f32_e32 v130, v130
	v_rcp_f32_e32 v132, v132
	v_cndmask_b32_e32 v42, 1.0, v42, vcc
	v_cmp_lt_i32_e32 vcc, 24, v134
	v_mul_f32_e32 v44, v135, v44
	v_mul_f32_e32 v45, v45, v37
	v_cndmask_b32_e32 v34, 1.0, v34, vcc
	v_cndmask_b32_e32 v44, 0, v44, vcc
	v_cmp_lt_i32_e32 vcc, 25, v134
	v_mul_f32_e32 v37, v135, v37
	v_mul_f32_e32 v46, v46, v130
	v_cndmask_b32_e32 v45, 1.0, v45, vcc
	v_cndmask_b32_e32 v37, 0, v37, vcc
	v_cmp_lt_i32_e32 vcc, 26, v134
	v_mul_f32_e32 v47, v47, v132
	v_cndmask_b32_e64 v47, 1.0, v47, s[0:1]
	v_cndmask_b32_e32 v46, 1.0, v46, vcc
	v_mul_f32_e32 v34, v34, v45
	v_mul_f32_e32 v134, v46, v47
	v_mul_f32_e32 v134, v34, v134
	v_mov_b32_e32 v148, v134
	v_mov_b32_e32 v240, v134
	s_nop 1
	v_permlane32_swap_b32_e32 v148, v240
	v_cndmask_b32_e64 v148, v148, v240, s[2:3]
	v_mul_f32_e32 v34, v135, v130
	v_cndmask_b32_e32 v149, 0, v34, vcc
	v_mul_f32_e32 v34, v135, v132
	v_cndmask_b32_e64 v34, 0, v34, s[0:1]
	s_waitcnt lgkmcnt(0)
	v_cndmask_b32_e64 v130, 1.0, v148, s[2:3]
	v_mul_f32_e32 v135, v34, v130
	v_mul_f32_e32 v34, v36, v145
	v_mul_f32_e32 v36, v43, v42
	v_mul_f32_e32 v36, v34, v36
	v_mul_f32_e32 v32, v32, v38
	v_mul_f32_e32 v34, v142, v39
	v_mov_b32_e32 v150, v36
	v_mov_b32_e32 v240, v36
	s_nop 1
	v_permlane32_swap_b32_e32 v150, v240
	v_cndmask_b32_e64 v150, v150, v240, s[2:3]
	v_mul_f32_e32 v34, v32, v34
	v_mul_f32_e32 v47, v47, v130
	v_mov_b32_e32 v130, v34
	v_mov_b32_e32 v240, v34
	s_nop 1
	v_permlane32_swap_b32_e32 v130, v240
	v_cndmask_b32_e64 v130, v130, v240, s[2:3]
	v_mul_f32_e32 v46, v46, v47
	v_mul_f32_e32 v32, v134, v148
	s_waitcnt lgkmcnt(1)
	v_mul_f32_e32 v132, v36, v150
	v_mul_f32_e32 v45, v45, v46
	v_mul_f32_e32 v46, v37, v46
	s_waitcnt lgkmcnt(0)
	v_cndmask_b32_e64 v134, 1.0, v130, s[2:3]
	v_pk_mul_f32 v[36:37], v[32:33], v[132:133]
	v_pk_mul_f32 v[34:35], v[34:35], v[130:131]
	v_mul_f32_e32 v132, v36, v134
	v_mul_f32_e32 v134, v39, v132
	v_mul_f32_e32 v142, v142, v134
	v_mul_f32_e32 v148, v38, v142
	v_pk_mul_f32 v[38:39], v[34:35], v[36:37]
	v_mov_b32_e32 v130, v39
	v_mov_b32_e32 v240, v39
	s_nop 1
	v_permlane32_swap_b32_e32 v130, v240
	v_cndmask_b32_e64 v130, v130, v240, s[2:3]
	v_mul_f32_e32 v37, v40, v132
	v_mul_f32_e32 v40, v143, v134
	v_mul_f32_e32 v36, v141, v142
	v_mul_f32_e32 v132, v140, v148
	s_waitcnt lgkmcnt(0)
	v_cndmask_b32_e64 v34, 1.0, v130, s[2:3]
	v_mul_f32_e32 v34, v38, v34
	v_mul_f32_e32 v35, v133, v34
	v_mul_f32_e32 v33, v33, v35
	v_mul_f32_e32 v131, v131, v33
	v_mul_f32_e32 v133, v136, v34
	v_mul_f32_e32 v35, v139, v35
	v_mul_f32_e32 v33, v137, v33
	v_mul_f32_e32 v34, v138, v131
	v_cvt_pk_bf16_f32 v34, v34, v33
	v_cvt_pk_bf16_f32 v35, v35, v133
	v_cvt_pk_bf16_f32 v36, v132, v36
	v_cvt_pk_bf16_f32 v37, v40, v37
	v_cndmask_b32_e64 v33, 1.0, v150, s[2:3]
	v_mul_f32_e32 v32, v32, v33
	v_mfma_f32_32x32x16_bf16 v[16:31], v[92:95], v[34:37], v[16:31]
	v_mul_f32_e32 v33, v42, v32
	v_mul_f32_e32 v42, v43, v33
	v_mul_f32_e32 v43, v145, v42
	v_mul_f32_e32 v47, v149, v47
	v_mul_f32_e32 v40, v44, v45
	v_mul_f32_e32 v44, v147, v32
	v_mul_f32_e32 v33, v146, v33
	v_mfma_f32_32x32x16_bf16 v[0:15], v[88:91], v[34:37], v[0:15]
	v_mul_f32_e32 v32, v41, v42
	v_mul_f32_e32 v34, v144, v43
	v_cvt_pk_bf16_f32 v32, v34, v32
	v_cvt_pk_bf16_f32 v33, v33, v44
	v_cvt_pk_bf16_f32 v34, v40, v46
	v_cvt_pk_bf16_f32 v35, v47, v135
	v_mul_f32_e32 v36, v39, v130
	v_mul_f32_e32 v36, v38, v36
	v_mfma_f32_32x32x16_bf16 v[16:31], v[84:87], v[32:35], v[16:31]
	v_log_f32_e32 v36, v36
	s_nop 0
	v_add_f32_e32 v125, v125, v36
	v_mfma_f32_32x32x16_bf16 v[0:15], v[80:83], v[32:35], v[0:15]
; __device__ __forceinline__ void sb_unit(const Frame& F, int b, int hd, int qi, int dry) {
;     ...
;             float run = C;
;             if (!meta && key0 + 96 < tqw + 31) SB_HALF(96);
;             if (!meta && key0 + 64 < tqw + 31 && __any(run >= SB_DEAD)) SB_HALF(64);
;             if (!meta && key0 + 32 < tqw + 31 && __any(run >= SB_DEAD)) SB_HALF(32);
.LBB0_344:
	s_or_b32 s0, s35, 1
	s_cmp_ge_i32 s0, s26
	s_cselect_b64 s[0:1], -1, 0
	s_or_b64 s[0:1], s[18:19], s[0:1]
	s_and_b64 vcc, exec, s[0:1]
	s_cbranch_vccnz .LBB0_347
	v_cmp_le_f32_e32 vcc, s22, v125
	s_cbranch_vccz .LBB0_347
	ds_read_b128 v[32:35], v129 offset:4608
	ds_read_b128 v[80:83], v129 offset:4640
	v_exp_f32_e32 v135, v125
	v_sub_u32_e32 v134, v126, v127
	v_cmp_lt_i32_e32 vcc, 0, v134
	s_waitcnt lgkmcnt(1)
	v_mfma_f32_32x32x16_bf16 v[32:47], v[32:35], v[48:51], 0
	v_cmp_lt_i32_e64 s[0:1], 27, v134
	s_waitcnt lgkmcnt(0)
	v_mfma_f32_32x32x16_bf16 v[32:47], v[80:83], v[52:55], v[32:47]
	ds_read_b128 v[80:83], v129 offset:4672
	ds_read_b128 v[130:133], v129 offset:4704
	s_waitcnt lgkmcnt(1)
	v_mfma_f32_32x32x16_bf16 v[32:47], v[80:83], v[56:59], v[32:47]
	ds_read_b64_tr_b16 v[92:93], v128 offset:43008
	ds_read_b64_tr_b16 v[94:95], v128 offset:44544
	ds_read_b64_tr_b16 v[90:91], v128 offset:44608
	ds_read_b64_tr_b16 v[88:89], v128 offset:43072
	ds_read_b64_tr_b16 v[84:85], v128 offset:46080
	ds_read_b64_tr_b16 v[86:87], v128 offset:47616
	ds_read_b64_tr_b16 v[82:83], v128 offset:47680
	ds_read_b64_tr_b16 v[80:81], v128 offset:46144
	s_waitcnt lgkmcnt(8)
	v_mfma_f32_32x32x16_bf16 v[32:47], v[130:133], v[60:63], v[32:47]
	s_nop 11
	v_min_f32_e64 v32, -v32, s60
	v_min_f32_e64 v33, -v33, s60
	v_exp_f32_e32 v32, v32
	v_min_f32_e64 v34, -v34, s60
	v_exp_f32_e32 v33, v33
	v_exp_f32_e32 v34, v34
	v_min_f32_e64 v35, -v35, s60
	v_exp_f32_e32 v130, v35
	v_add_f32_e32 v35, 1.0, v32
	v_add_f32_e32 v131, 1.0, v33
	v_rcp_f32_e32 v35, v35
	v_add_f32_e32 v132, 1.0, v34
	v_rcp_f32_e32 v131, v131
	v_min_f32_e64 v36, -v36, s60
	v_rcp_f32_e32 v132, v132
	v_exp_f32_e32 v36, v36
	v_add_f32_e32 v133, 1.0, v130
	v_rcp_f32_e32 v136, v133
	v_mul_f32_e32 v32, v32, v35
	v_mul_f32_e32 v133, v135, v35
	v_mul_f32_e32 v33, v33, v131
	v_mul_f32_e32 v137, v135, v131
	v_cndmask_b32_e32 v35, 1.0, v32, vcc
	v_cndmask_b32_e32 v138, 0, v133, vcc
	v_cmp_lt_i32_e32 vcc, 1, v134
	v_mul_f32_e32 v34, v34, v132
	v_mul_f32_e32 v32, v135, v132
	v_cndmask_b32_e32 v131, 1.0, v33, vcc
	v_cndmask_b32_e32 v137, 0, v137, vcc
	v_cmp_lt_i32_e32 vcc, 2, v134
	v_min_f32_e64 v39, -v39, s60
	v_cndmask_b32_e32 v33, 1.0, v34, vcc
	v_add_f32_e32 v34, 1.0, v36
	v_rcp_f32_e32 v34, v34
	v_cndmask_b32_e32 v139, 0, v32, vcc
	v_mul_f32_e32 v32, v130, v136
	v_cmp_lt_i32_e32 vcc, 3, v134
	v_exp_f32_e32 v39, v39
	v_cndmask_b32_e32 v133, 1.0, v32, vcc
	v_mul_f32_e32 v32, v135, v136
	v_cndmask_b32_e32 v136, 0, v32, vcc
	v_mul_f32_e32 v32, v36, v34
	v_min_f32_e64 v36, -v37, s60
	v_exp_f32_e32 v36, v36
	v_cmp_lt_i32_e32 vcc, 8, v134
	v_mul_f32_e32 v34, v135, v34
	v_cndmask_b32_e32 v140, 0, v34, vcc
	v_add_f32_e32 v34, 1.0, v36
	v_rcp_f32_e32 v34, v34
	v_min_f32_e64 v37, -v38, s60
	v_exp_f32_e32 v37, v37
	v_cndmask_b32_e32 v32, 1.0, v32, vcc
	v_mul_f32_e32 v36, v36, v34
	v_cmp_lt_i32_e32 vcc, 9, v134
	v_mul_f32_e32 v34, v135, v34
	v_min_f32_e64 v42, -v42, s60
	v_cndmask_b32_e32 v38, 1.0, v36, vcc
	v_add_f32_e32 v36, 1.0, v37
	v_rcp_f32_e32 v36, v36
	v_cndmask_b32_e32 v141, 0, v34, vcc
	v_cmp_lt_i32_e32 vcc, 10, v134
	v_exp_f32_e32 v42, v42
	v_mul_f32_e32 v34, v37, v36
	v_add_f32_e32 v37, 1.0, v39
	v_rcp_f32_e32 v37, v37
	v_cndmask_b32_e32 v142, 1.0, v34, vcc
	v_mul_f32_e32 v34, v135, v36
	v_cndmask_b32_e32 v143, 0, v34, vcc
	v_mul_f32_e32 v34, v39, v37
	v_cmp_lt_i32_e32 vcc, 11, v134
	v_min_f32_e64 v36, -v40, s60
	v_exp_f32_e32 v36, v36
	v_cndmask_b32_e32 v39, 1.0, v34, vcc
	v_mul_f32_e32 v34, v135, v37
	v_min_f32_e64 v37, -v41, s60
	v_exp_f32_e32 v37, v37
	v_cndmask_b32_e32 v40, 0, v34, vcc
	v_add_f32_e32 v34, 1.0, v36
	v_rcp_f32_e32 v34, v34
	v_add_f32_e32 v41, 1.0, v37
	v_rcp_f32_e32 v41, v41
	v_cmp_lt_i32_e32 vcc, 16, v134
	v_mul_f32_e32 v36, v36, v34
	v_mul_f32_e32 v34, v135, v34
	v_cndmask_b32_e32 v144, 0, v34, vcc
	v_mul_f32_e32 v34, v37, v41
	v_add_f32_e32 v37, 1.0, v42
	v_rcp_f32_e32 v37, v37
	v_cndmask_b32_e32 v36, 1.0, v36, vcc
	v_cmp_lt_i32_e32 vcc, 17, v134
	v_min_f32_e64 v45, -v45, s60
	v_cndmask_b32_e32 v145, 1.0, v34, vcc
	v_mul_f32_e32 v34, v135, v41
	v_cndmask_b32_e32 v41, 0, v34, vcc
	v_mul_f32_e32 v34, v42, v37
	v_cmp_lt_i32_e32 vcc, 18, v134
	v_min_f32_e64 v42, -v43, s60
	v_exp_f32_e32 v42, v42
	v_cndmask_b32_e32 v43, 1.0, v34, vcc
	v_mul_f32_e32 v34, v135, v37
	v_min_f32_e64 v37, -v44, s60
	v_exp_f32_e32 v37, v37
	v_cndmask_b32_e32 v146, 0, v34, vcc
	v_add_f32_e32 v34, 1.0, v42
	v_rcp_f32_e32 v34, v34
	v_add_f32_e32 v44, 1.0, v37
	v_rcp_f32_e32 v44, v44
	v_exp_f32_e32 v45, v45
	v_min_f32_e64 v46, -v46, s60
	v_min_f32_e64 v47, -v47, s60
	v_exp_f32_e32 v46, v46
	v_exp_f32_e32 v47, v47
	v_mul_f32_e32 v42, v42, v34
	v_cmp_lt_i32_e32 vcc, 19, v134
	v_mul_f32_e32 v34, v135, v34
	v_add_f32_e32 v130, 1.0, v46
	v_cndmask_b32_e32 v147, 0, v34, vcc
	v_mul_f32_e32 v34, v37, v44
	v_add_f32_e32 v37, 1.0, v45
	v_rcp_f32_e32 v37, v37
	v_add_f32_e32 v132, 1.0, v47
	v_rcp_f32_e32 v130, v130
	v_rcp_f32_e32 v132, v132
	v_cndmask_b32_e32 v42, 1.0, v42, vcc
	v_cmp_lt_i32_e32 vcc, 24, v134
	v_mul_f32_e32 v44, v135, v44
	v_mul_f32_e32 v45, v45, v37
	v_cndmask_b32_e32 v34, 1.0, v34, vcc
	v_cndmask_b32_e32 v44, 0, v44, vcc
	v_cmp_lt_i32_e32 vcc, 25, v134
	v_mul_f32_e32 v37, v135, v37
	v_mul_f32_e32 v46, v46, v130
	v_cndmask_b32_e32 v45, 1.0, v45, vcc
	v_cndmask_b32_e32 v37, 0, v37, vcc
	v_cmp_lt_i32_e32 vcc, 26, v134
	v_mul_f32_e32 v47, v47, v132
	v_cndmask_b32_e64 v47, 1.0, v47, s[0:1]
	v_cndmask_b32_e32 v46, 1.0, v46, vcc
	v_mul_f32_e32 v34, v34, v45
	v_mul_f32_e32 v134, v46, v47
	v_mul_f32_e32 v134, v34, v134
	v_mov_b32_e32 v148, v134
	v_mov_b32_e32 v240, v134
	s_nop 1
	v_permlane32_swap_b32_e32 v148, v240
	v_cndmask_b32_e64 v148, v148, v240, s[2:3]
	v_mul_f32_e32 v34, v135, v130
	v_cndmask_b32_e32 v149, 0, v34, vcc
	v_mul_f32_e32 v34, v135, v132
	v_cndmask_b32_e64 v34, 0, v34, s[0:1]
	s_waitcnt lgkmcnt(0)
; __device__ __forceinline__ void sb_unit(const Frame& F, int b, int hd, int qi, int dry) {
;     ...
;             float run = C;
;             if (!meta && key0 + 96 < tqw + 31) SB_HALF(96);
;             if (!meta && key0 + 64 < tqw + 31 && __any(run >= SB_DEAD)) SB_HALF(64);
;             if (!meta && key0 + 32 < tqw + 31 && __any(run >= SB_DEAD)) SB_HALF(32);
;             if (__any(run >= SB_DEAD)) SB_HALF(0);
	v_cndmask_b32_e64 v130, 1.0, v148, s[2:3]
	v_mul_f32_e32 v135, v34, v130
	v_mul_f32_e32 v34, v36, v145
	v_mul_f32_e32 v36, v43, v42
	v_mul_f32_e32 v36, v34, v36
	v_mul_f32_e32 v32, v32, v38
	v_mul_f32_e32 v34, v142, v39
	v_mov_b32_e32 v150, v36
	v_mov_b32_e32 v240, v36
	s_nop 1
	v_permlane32_swap_b32_e32 v150, v240
	v_cndmask_b32_e64 v150, v150, v240, s[2:3]
	v_mul_f32_e32 v34, v32, v34
	v_mul_f32_e32 v47, v47, v130
	v_mov_b32_e32 v130, v34
	v_mov_b32_e32 v240, v34
	s_nop 1
	v_permlane32_swap_b32_e32 v130, v240
	v_cndmask_b32_e64 v130, v130, v240, s[2:3]
	v_mul_f32_e32 v46, v46, v47
	v_mul_f32_e32 v32, v134, v148
	s_waitcnt lgkmcnt(1)
	v_mul_f32_e32 v132, v36, v150
	v_mul_f32_e32 v45, v45, v46
	v_mul_f32_e32 v46, v37, v46
	s_waitcnt lgkmcnt(0)
	v_cndmask_b32_e64 v134, 1.0, v130, s[2:3]
	v_pk_mul_f32 v[36:37], v[32:33], v[132:133]
	v_pk_mul_f32 v[34:35], v[34:35], v[130:131]
	v_mul_f32_e32 v132, v36, v134
	v_mul_f32_e32 v134, v39, v132
	v_mul_f32_e32 v142, v142, v134
	v_mul_f32_e32 v148, v38, v142
	v_pk_mul_f32 v[38:39], v[34:35], v[36:37]
	v_mov_b32_e32 v130, v39
	v_mov_b32_e32 v240, v39
	s_nop 1
	v_permlane32_swap_b32_e32 v130, v240
	v_cndmask_b32_e64 v130, v130, v240, s[2:3]
	v_mul_f32_e32 v37, v40, v132
	v_mul_f32_e32 v40, v143, v134
	v_mul_f32_e32 v36, v141, v142
	v_mul_f32_e32 v132, v140, v148
	s_waitcnt lgkmcnt(0)
	v_cndmask_b32_e64 v34, 1.0, v130, s[2:3]
	v_mul_f32_e32 v34, v38, v34
	v_mul_f32_e32 v35, v133, v34
	v_mul_f32_e32 v33, v33, v35
	v_mul_f32_e32 v131, v131, v33
	v_mul_f32_e32 v133, v136, v34
	v_mul_f32_e32 v35, v139, v35
	v_mul_f32_e32 v33, v137, v33
	v_mul_f32_e32 v34, v138, v131
	v_cvt_pk_bf16_f32 v34, v34, v33
	v_cvt_pk_bf16_f32 v35, v35, v133
	v_cvt_pk_bf16_f32 v36, v132, v36
	v_cvt_pk_bf16_f32 v37, v40, v37
	v_cndmask_b32_e64 v33, 1.0, v150, s[2:3]
	v_mul_f32_e32 v32, v32, v33
	v_mfma_f32_32x32x16_bf16 v[16:31], v[92:95], v[34:37], v[16:31]
	v_mul_f32_e32 v33, v42, v32
	v_mul_f32_e32 v42, v43, v33
	v_mul_f32_e32 v43, v145, v42
	v_mul_f32_e32 v47, v149, v47
	v_mul_f32_e32 v40, v44, v45
	v_mul_f32_e32 v44, v147, v32
	v_mul_f32_e32 v33, v146, v33
	v_mfma_f32_32x32x16_bf16 v[0:15], v[88:91], v[34:37], v[0:15]
	v_mul_f32_e32 v32, v41, v42
	v_mul_f32_e32 v34, v144, v43
	v_cvt_pk_bf16_f32 v32, v34, v32
	v_cvt_pk_bf16_f32 v33, v33, v44
	v_cvt_pk_bf16_f32 v34, v40, v46
	v_cvt_pk_bf16_f32 v35, v47, v135
	v_mul_f32_e32 v36, v39, v130
	v_mul_f32_e32 v36, v38, v36
	v_mfma_f32_32x32x16_bf16 v[16:31], v[84:87], v[32:35], v[16:31]
	v_log_f32_e32 v36, v36
	s_nop 0
	v_add_f32_e32 v125, v125, v36
	v_mfma_f32_32x32x16_bf16 v[0:15], v[80:83], v[32:35], v[0:15]
.LBB0_347:
	v_cmp_le_f32_e32 vcc, s22, v125
	s_cbranch_vccz .LBB0_349
	ds_read_b128 v[32:35], v129
	ds_read_b128 v[80:83], v129 offset:32
	s_waitcnt lgkmcnt(1)
	v_mfma_f32_32x32x16_bf16 v[32:47], v[32:35], v[48:51], 0
	s_waitcnt lgkmcnt(0)
	v_mfma_f32_32x32x16_bf16 v[32:47], v[80:83], v[52:55], v[32:47]
	ds_read_b128 v[80:83], v129 offset:64
	ds_read_b128 v[130:133], v129 offset:96
	v_cndmask_b32_e64 v129, v114, 16, s[18:19]
	v_sub_u32_e32 v127, v129, v127
	v_cmp_lt_i32_e32 vcc, 0, v127
	v_cmp_lt_i32_e64 s[0:1], 27, v127
	s_waitcnt lgkmcnt(1)
	v_mfma_f32_32x32x16_bf16 v[32:47], v[80:83], v[56:59], v[32:47]
	ds_read_b64_tr_b16 v[92:93], v128 offset:36864
	ds_read_b64_tr_b16 v[94:95], v128 offset:38400
	ds_read_b64_tr_b16 v[90:91], v128 offset:38464
	ds_read_b64_tr_b16 v[88:89], v128 offset:36928
	ds_read_b64_tr_b16 v[84:85], v128 offset:39936
	ds_read_b64_tr_b16 v[86:87], v128 offset:41472
	ds_read_b64_tr_b16 v[82:83], v128 offset:41536
	ds_read_b64_tr_b16 v[80:81], v128 offset:40000
	v_exp_f32_e32 v128, v125
	s_waitcnt lgkmcnt(8)
	v_mfma_f32_32x32x16_bf16 v[32:47], v[130:133], v[60:63], v[32:47]
	s_nop 11
	v_min_f32_e64 v32, -v32, s60
	v_min_f32_e64 v33, -v33, s60
	v_exp_f32_e32 v32, v32
	v_min_f32_e64 v34, -v34, s60
	v_exp_f32_e32 v33, v33
	v_exp_f32_e32 v34, v34
	v_min_f32_e64 v35, -v35, s60
	v_exp_f32_e32 v130, v35
	v_add_f32_e32 v35, 1.0, v32
	v_add_f32_e32 v129, 1.0, v33
	v_rcp_f32_e32 v35, v35
	v_add_f32_e32 v131, 1.0, v34
	v_rcp_f32_e32 v129, v129
	v_rcp_f32_e32 v131, v131
	v_add_f32_e32 v132, 1.0, v130
	v_rcp_f32_e32 v132, v132
	v_mul_f32_e32 v32, v32, v35
	v_mul_f32_e32 v133, v128, v35
	v_min_f32_e64 v36, -v36, s60
	v_mul_f32_e32 v33, v33, v129
	v_mul_f32_e32 v134, v128, v129
	v_cndmask_b32_e32 v35, 1.0, v32, vcc
	v_cndmask_b32_e32 v133, 0, v133, vcc
	v_cmp_lt_i32_e32 vcc, 1, v127
	v_mul_f32_e32 v34, v34, v131
	v_exp_f32_e32 v32, v36
	v_cndmask_b32_e32 v129, 1.0, v33, vcc
	v_cndmask_b32_e32 v134, 0, v134, vcc
	v_cmp_lt_i32_e32 vcc, 2, v127
	v_add_f32_e32 v36, 1.0, v32
	v_rcp_f32_e32 v36, v36
	v_cndmask_b32_e32 v33, 1.0, v34, vcc
	v_mul_f32_e32 v34, v128, v131
	v_cndmask_b32_e32 v135, 0, v34, vcc
	v_mul_f32_e32 v34, v130, v132
	v_cmp_lt_i32_e32 vcc, 3, v127
	v_mul_f32_e32 v32, v32, v36
	v_mul_f32_e32 v36, v128, v36
	v_cndmask_b32_e32 v131, 1.0, v34, vcc
	v_mul_f32_e32 v34, v128, v132
	v_cndmask_b32_e32 v132, 0, v34, vcc
	v_min_f32_e64 v34, -v37, s60
	v_exp_f32_e32 v34, v34
	v_cmp_lt_i32_e32 vcc, 8, v127
	v_min_f32_e64 v37, -v38, s60
	v_cndmask_b32_e32 v136, 0, v36, vcc
	v_add_f32_e32 v36, 1.0, v34
	v_rcp_f32_e32 v36, v36
	v_exp_f32_e32 v37, v37
	v_cndmask_b32_e32 v32, 1.0, v32, vcc
	v_cmp_lt_i32_e32 vcc, 9, v127
	v_mul_f32_e32 v34, v34, v36
	v_cndmask_b32_e32 v38, 1.0, v34, vcc
	v_add_f32_e32 v34, 1.0, v37
	v_min_f32_e64 v39, -v39, s60
	v_rcp_f32_e32 v34, v34
	v_exp_f32_e32 v39, v39
; __device__ __forceinline__ void sb_unit(const Frame& F, int b, int hd, int qi, int dry) {
;     ...
;             float run = C;
;             if (!meta && key0 + 96 < tqw + 31) SB_HALF(96);
;             if (!meta && key0 + 64 < tqw + 31 && __any(run >= SB_DEAD)) SB_HALF(64);
;             if (!meta && key0 + 32 < tqw + 31 && __any(run >= SB_DEAD)) SB_HALF(32);
;             if (__any(run >= SB_DEAD)) SB_HALF(0);
	v_mul_f32_e32 v36, v128, v36
	v_cndmask_b32_e32 v137, 0, v36, vcc
	v_mul_f32_e32 v36, v37, v34
	v_add_f32_e32 v37, 1.0, v39
	v_rcp_f32_e32 v37, v37
	v_cmp_lt_i32_e32 vcc, 10, v127
	v_mul_f32_e32 v34, v128, v34
	v_cndmask_b32_e32 v138, 1.0, v36, vcc
	v_cndmask_b32_e32 v139, 0, v34, vcc
	v_mul_f32_e32 v34, v39, v37
	v_cmp_lt_i32_e32 vcc, 11, v127
	v_min_f32_e64 v36, -v40, s60
	v_exp_f32_e32 v36, v36
	v_cndmask_b32_e32 v39, 1.0, v34, vcc
	v_mul_f32_e32 v34, v128, v37
	v_min_f32_e64 v37, -v41, s60
	v_exp_f32_e32 v37, v37
	v_cndmask_b32_e32 v40, 0, v34, vcc
	v_add_f32_e32 v34, 1.0, v36
	v_rcp_f32_e32 v34, v34
	v_add_f32_e32 v41, 1.0, v37
	v_min_f32_e64 v42, -v42, s60
	v_rcp_f32_e32 v41, v41
	v_exp_f32_e32 v42, v42
	v_mul_f32_e32 v36, v36, v34
	v_cmp_lt_i32_e32 vcc, 16, v127
	v_mul_f32_e32 v34, v128, v34
	v_cndmask_b32_e32 v140, 0, v34, vcc
	v_mul_f32_e32 v34, v37, v41
	v_add_f32_e32 v37, 1.0, v42
	v_rcp_f32_e32 v37, v37
	v_cndmask_b32_e32 v36, 1.0, v36, vcc
	v_cmp_lt_i32_e32 vcc, 17, v127
	v_min_f32_e64 v45, -v45, s60
	v_cndmask_b32_e32 v141, 1.0, v34, vcc
	v_mul_f32_e32 v34, v128, v41
	v_cndmask_b32_e32 v41, 0, v34, vcc
	v_mul_f32_e32 v34, v42, v37
	v_cmp_lt_i32_e32 vcc, 18, v127
	v_min_f32_e64 v42, -v43, s60
	v_exp_f32_e32 v42, v42
	v_cndmask_b32_e32 v43, 1.0, v34, vcc
	v_mul_f32_e32 v34, v128, v37
	v_min_f32_e64 v37, -v44, s60
	v_exp_f32_e32 v37, v37
	v_cndmask_b32_e32 v142, 0, v34, vcc
	v_add_f32_e32 v34, 1.0, v42
	v_rcp_f32_e32 v34, v34
	v_add_f32_e32 v44, 1.0, v37
	v_rcp_f32_e32 v44, v44
	v_exp_f32_e32 v45, v45
	v_min_f32_e64 v46, -v46, s60
	v_min_f32_e64 v47, -v47, s60
	v_exp_f32_e32 v46, v46
	v_exp_f32_e32 v47, v47
	v_mul_f32_e32 v42, v42, v34
	v_cmp_lt_i32_e32 vcc, 19, v127
	v_mul_f32_e32 v34, v128, v34
	v_add_f32_e32 v130, 1.0, v46
	v_cndmask_b32_e32 v143, 0, v34, vcc
	v_mul_f32_e32 v34, v37, v44
	v_add_f32_e32 v37, 1.0, v45
	v_rcp_f32_e32 v37, v37
	v_add_f32_e32 v144, 1.0, v47
	v_rcp_f32_e32 v130, v130
	v_rcp_f32_e32 v144, v144
	v_cndmask_b32_e32 v42, 1.0, v42, vcc
	v_cmp_lt_i32_e32 vcc, 24, v127
	v_mul_f32_e32 v44, v128, v44
	v_mul_f32_e32 v45, v45, v37
	v_cndmask_b32_e32 v34, 1.0, v34, vcc
	v_cndmask_b32_e32 v44, 0, v44, vcc
	v_cmp_lt_i32_e32 vcc, 25, v127
	v_mul_f32_e32 v37, v128, v37
	v_mul_f32_e32 v46, v46, v130
	v_cndmask_b32_e32 v45, 1.0, v45, vcc
	v_cndmask_b32_e32 v37, 0, v37, vcc
	v_cmp_lt_i32_e32 vcc, 26, v127
	v_mul_f32_e32 v47, v47, v144
	v_cndmask_b32_e64 v47, 1.0, v47, s[0:1]
	v_cndmask_b32_e32 v46, 1.0, v46, vcc
	v_mul_f32_e32 v34, v34, v45
	v_mul_f32_e32 v127, v46, v47
	v_mul_f32_e32 v127, v34, v127
	v_mov_b32_e32 v145, v127
	v_mov_b32_e32 v240, v127
	s_nop 1
	v_permlane32_swap_b32_e32 v145, v240
	v_cndmask_b32_e64 v145, v145, v240, s[2:3]
	v_mul_f32_e32 v34, v128, v130
	v_cndmask_b32_e32 v130, 0, v34, vcc
	v_mul_f32_e32 v34, v128, v144
	v_cndmask_b32_e64 v34, 0, v34, s[0:1]
	s_waitcnt lgkmcnt(0)
	v_cndmask_b32_e64 v128, 1.0, v145, s[2:3]
	v_mul_f32_e32 v144, v34, v128
	v_mul_f32_e32 v34, v36, v141
	v_mul_f32_e32 v36, v43, v42
	v_mul_f32_e32 v36, v34, v36
	v_mul_f32_e32 v32, v32, v38
	v_mul_f32_e32 v34, v138, v39
	v_mov_b32_e32 v146, v36
	v_mov_b32_e32 v240, v36
	s_nop 1
	v_permlane32_swap_b32_e32 v146, v240
	v_cndmask_b32_e64 v146, v146, v240, s[2:3]
	v_mul_f32_e32 v34, v32, v34
	v_mul_f32_e32 v47, v47, v128
	v_mov_b32_e32 v128, v34
	v_mov_b32_e32 v240, v34
	s_nop 1
	v_permlane32_swap_b32_e32 v128, v240
	v_cndmask_b32_e64 v128, v128, v240, s[2:3]
	v_mul_f32_e32 v46, v46, v47
	v_mul_f32_e32 v47, v130, v47
	v_mul_f32_e32 v32, v127, v145
	s_waitcnt lgkmcnt(1)
	v_mul_f32_e32 v130, v36, v146
	v_mul_f32_e32 v45, v45, v46
	v_mul_f32_e32 v46, v37, v46
	s_waitcnt lgkmcnt(0)
	v_cndmask_b32_e64 v127, 1.0, v128, s[2:3]
	v_pk_mul_f32 v[36:37], v[32:33], v[130:131]
	v_pk_mul_f32 v[34:35], v[34:35], v[128:129]
	v_mul_f32_e32 v127, v36, v127
	v_mul_f32_e32 v130, v39, v127
	v_mul_f32_e32 v138, v138, v130
	v_mul_f32_e32 v145, v38, v138
	v_pk_mul_f32 v[38:39], v[34:35], v[36:37]
	v_mov_b32_e32 v128, v39
	v_mov_b32_e32 v240, v39
	s_nop 1
	v_permlane32_swap_b32_e32 v128, v240
	v_cndmask_b32_e64 v128, v128, v240, s[2:3]
	v_mul_f32_e32 v37, v40, v127
	v_mul_f32_e32 v40, v139, v130
	v_mul_f32_e32 v36, v137, v138
	v_mul_f32_e32 v127, v136, v145
	s_waitcnt lgkmcnt(0)
	v_cndmask_b32_e64 v34, 1.0, v128, s[2:3]
	v_mul_f32_e32 v34, v38, v34
	v_mul_f32_e32 v35, v131, v34
	v_mul_f32_e32 v33, v33, v35
	v_mul_f32_e32 v129, v129, v33
	v_mul_f32_e32 v130, v132, v34
	v_mul_f32_e32 v35, v135, v35
	v_mul_f32_e32 v33, v134, v33
	v_mul_f32_e32 v34, v133, v129
	v_cvt_pk_bf16_f32 v34, v34, v33
	v_cvt_pk_bf16_f32 v35, v35, v130
	v_cvt_pk_bf16_f32 v36, v127, v36
	v_cvt_pk_bf16_f32 v37, v40, v37
	v_cndmask_b32_e64 v33, 1.0, v146, s[2:3]
	v_mul_f32_e32 v32, v32, v33
	v_mfma_f32_32x32x16_bf16 v[16:31], v[92:95], v[34:37], v[16:31]
	v_mul_f32_e32 v33, v42, v32
	v_mul_f32_e32 v42, v43, v33
	v_mul_f32_e32 v43, v141, v42
	v_mul_f32_e32 v40, v44, v45
	v_mul_f32_e32 v44, v143, v32
	v_mul_f32_e32 v33, v142, v33
	v_mul_f32_e32 v32, v41, v42
	v_mfma_f32_32x32x16_bf16 v[0:15], v[88:91], v[34:37], v[0:15]
	v_mul_f32_e32 v34, v140, v43
	v_cvt_pk_bf16_f32 v32, v34, v32
	v_cvt_pk_bf16_f32 v33, v33, v44
	v_cvt_pk_bf16_f32 v34, v40, v46
	v_cvt_pk_bf16_f32 v35, v47, v144
	v_mul_f32_e32 v36, v39, v128
	v_mul_f32_e32 v36, v38, v36
	v_mfma_f32_32x32x16_bf16 v[16:31], v[84:87], v[32:35], v[16:31]
	v_log_f32_e32 v36, v36
	s_nop 0
	v_add_f32_e32 v125, v125, v36
	v_mfma_f32_32x32x16_bf16 v[0:15], v[80:83], v[32:35], v[0:15]

; #define LAS __attribute__((address_space(3)))
; #define S_LOAD(key0) do { st0 = *(const u32x4*)(kg + (size_t)(key0) * 1024); st1 = *(const u32x4*)(kg + (size_t)((key0) + 64) * 1024); st2 = *(const u32x4*)(vg + (size_t)(key0) * 1024); st3 = *(const u32x4*)(vg + (size_t)((key0) + 64) * 1024); } while (0)
; __device__ __forceinline__ void sb_unit(const Frame& F, int b, int hd, int qi, int dry) {
;     ...
;     for (int it = 0; it < nt; ++it) {
;         const bool meta = (it > jmax);
;         const int key0 = meta ? 0 : NMETA + 128 * (jmax - it);
;         if (it + 1 < nt) { const int nk = (it + 1 > jmax) ? 0 : NMETA + 128 * (jmax - it - 1); S_LOAD(nk); }
;         if (!dead && (meta || key0 < tqw + 31)) {
;             const LAS unsigned char* kb = lds + kra + (it & 1) * SK_BUF;
;             const LAS unsigned char* vb = lds + vra + (it & 1) * SV_BUF;
;     ...
;             float run = C;
;             if (!meta && key0 + 96 < tqw + 31) SB_HALF(96);
.LBB0_360:
	s_xor_b64 s[0:1], s[0:1], -1
	s_andn2_b64 vcc, exec, s[0:1]
	s_mov_b64 s[0:1], -1
	s_cbranch_vccnz .LBB0_373
	s_add_i32 s34, s31, 0xffffff10
	s_cmp_gt_u32 s35, s27
	s_cselect_b64 s[18:19], -1, 0
	s_and_b64 s[0:1], s[18:19], exec
	s_cselect_b32 s34, 0, s34
	s_cmp_lt_i32 s34, s29
	s_cselect_b64 s[0:1], -1, 0
	s_or_b64 s[0:1], s[18:19], s[0:1]
	s_andn2_b64 vcc, exec, s[0:1]
	s_mov_b64 s[0:1], 0
	s_cbranch_vccnz .LBB0_373
	s_and_b32 s0, s35, 1
	s_mul_i32 s35, s0, 0x4800
	s_mul_i32 s36, s0, 0x6000
	s_or_b32 s0, s34, 0x41
	s_cmp_ge_i32 s0, s25
	s_cselect_b64 s[0:1], -1, 0
	s_or_b64 s[0:1], s[18:19], s[0:1]
	s_and_b64 vcc, exec, s[0:1]
	v_add_u32_e32 v129, s35, v118
	v_or_b32_e32 v127, s34, v205
	v_add_u32_e32 v128, s36, v119
	s_cbranch_vccnz .LBB0_364
	ds_read_b128 v[32:35], v129 offset:13824
	ds_read_b128 v[80:83], v129 offset:13856
	v_exp_f32_e32 v135, v126
	v_sub_u32_e32 v134, v115, v127
	v_cmp_lt_i32_e32 vcc, 0, v134
	s_waitcnt lgkmcnt(1)
	v_mfma_f32_32x32x16_bf16 v[32:47], v[32:35], v[48:51], 0
	v_cmp_lt_i32_e64 s[0:1], 27, v134
	s_waitcnt lgkmcnt(0)
	v_mfma_f32_32x32x16_bf16 v[32:47], v[80:83], v[52:55], v[32:47]
	ds_read_b128 v[80:83], v129 offset:13888
	ds_read_b128 v[130:133], v129 offset:13920
	s_waitcnt lgkmcnt(1)
	v_mfma_f32_32x32x16_bf16 v[32:47], v[80:83], v[56:59], v[32:47]
	ds_read_b64_tr_b16 v[92:93], v128 offset:55296
	ds_read_b64_tr_b16 v[94:95], v128 offset:56832
	ds_read_b64_tr_b16 v[90:91], v128 offset:56896
	ds_read_b64_tr_b16 v[88:89], v128 offset:55360
	ds_read_b64_tr_b16 v[84:85], v128 offset:58368
	ds_read_b64_tr_b16 v[86:87], v128 offset:59904
	ds_read_b64_tr_b16 v[82:83], v128 offset:59968
	ds_read_b64_tr_b16 v[80:81], v128 offset:58432
	s_waitcnt lgkmcnt(8)
	v_mfma_f32_32x32x16_bf16 v[32:47], v[130:133], v[60:63], v[32:47]
	s_nop 11
	v_min_f32_e64 v32, -v32, s60
	v_min_f32_e64 v33, -v33, s60
	v_exp_f32_e32 v32, v32
	v_min_f32_e64 v34, -v34, s60
	v_exp_f32_e32 v33, v33
	v_exp_f32_e32 v34, v34
	v_min_f32_e64 v35, -v35, s60
	v_exp_f32_e32 v130, v35
	v_add_f32_e32 v35, 1.0, v32
	v_add_f32_e32 v131, 1.0, v33
	v_rcp_f32_e32 v35, v35
	v_add_f32_e32 v132, 1.0, v34
	v_rcp_f32_e32 v131, v131
	v_min_f32_e64 v36, -v36, s60
	v_rcp_f32_e32 v132, v132
	v_exp_f32_e32 v36, v36
	v_add_f32_e32 v133, 1.0, v130
	v_rcp_f32_e32 v136, v133
	v_mul_f32_e32 v32, v32, v35
	v_mul_f32_e32 v133, v135, v35
	v_mul_f32_e32 v33, v33, v131
	v_mul_f32_e32 v137, v135, v131
	v_cndmask_b32_e32 v35, 1.0, v32, vcc
	v_cndmask_b32_e32 v138, 0, v133, vcc
	v_cmp_lt_i32_e32 vcc, 1, v134
	v_mul_f32_e32 v34, v34, v132
	v_mul_f32_e32 v32, v135, v132
	v_cndmask_b32_e32 v131, 1.0, v33, vcc
	v_cndmask_b32_e32 v137, 0, v137, vcc
	v_cmp_lt_i32_e32 vcc, 2, v134
	v_min_f32_e64 v39, -v39, s60
	v_cndmask_b32_e32 v33, 1.0, v34, vcc
	v_add_f32_e32 v34, 1.0, v36
	v_rcp_f32_e32 v34, v34
	v_cndmask_b32_e32 v139, 0, v32, vcc
	v_mul_f32_e32 v32, v130, v136
	v_cmp_lt_i32_e32 vcc, 3, v134
	v_exp_f32_e32 v39, v39
	v_cndmask_b32_e32 v133, 1.0, v32, vcc
	v_mul_f32_e32 v32, v135, v136
	v_cndmask_b32_e32 v136, 0, v32, vcc
	v_mul_f32_e32 v32, v36, v34
	v_min_f32_e64 v36, -v37, s60
	v_exp_f32_e32 v36, v36
	v_cmp_lt_i32_e32 vcc, 8, v134
	v_mul_f32_e32 v34, v135, v34
	v_cndmask_b32_e32 v140, 0, v34, vcc
	v_add_f32_e32 v34, 1.0, v36
	v_rcp_f32_e32 v34, v34
	v_min_f32_e64 v37, -v38, s60
	v_exp_f32_e32 v37, v37
	v_cndmask_b32_e32 v32, 1.0, v32, vcc
	v_mul_f32_e32 v36, v36, v34
	v_cmp_lt_i32_e32 vcc, 9, v134
	v_mul_f32_e32 v34, v135, v34
	v_min_f32_e64 v42, -v42, s60
	v_cndmask_b32_e32 v38, 1.0, v36, vcc
	v_add_f32_e32 v36, 1.0, v37
	v_rcp_f32_e32 v36, v36
	v_cndmask_b32_e32 v141, 0, v34, vcc
	v_cmp_lt_i32_e32 vcc, 10, v134
	v_exp_f32_e32 v42, v42
	v_mul_f32_e32 v34, v37, v36
	v_add_f32_e32 v37, 1.0, v39
	v_rcp_f32_e32 v37, v37
	v_cndmask_b32_e32 v142, 1.0, v34, vcc
	v_mul_f32_e32 v34, v135, v36
	v_cndmask_b32_e32 v143, 0, v34, vcc
	v_mul_f32_e32 v34, v39, v37
	v_cmp_lt_i32_e32 vcc, 11, v134
	v_min_f32_e64 v36, -v40, s60
	v_exp_f32_e32 v36, v36
	v_cndmask_b32_e32 v39, 1.0, v34, vcc
	v_mul_f32_e32 v34, v135, v37
	v_min_f32_e64 v37, -v41, s60
	v_exp_f32_e32 v37, v37
	v_cndmask_b32_e32 v40, 0, v34, vcc
	v_add_f32_e32 v34, 1.0, v36
	v_rcp_f32_e32 v34, v34
	v_add_f32_e32 v41, 1.0, v37
	v_rcp_f32_e32 v41, v41
	v_cmp_lt_i32_e32 vcc, 16, v134
	v_mul_f32_e32 v36, v36, v34
	v_mul_f32_e32 v34, v135, v34
	v_cndmask_b32_e32 v144, 0, v34, vcc
	v_mul_f32_e32 v34, v37, v41
	v_add_f32_e32 v37, 1.0, v42
	v_rcp_f32_e32 v37, v37
	v_cndmask_b32_e32 v36, 1.0, v36, vcc
	v_cmp_lt_i32_e32 vcc, 17, v134
	v_min_f32_e64 v45, -v45, s60
	v_cndmask_b32_e32 v145, 1.0, v34, vcc
	v_mul_f32_e32 v34, v135, v41
	v_cndmask_b32_e32 v41, 0, v34, vcc
	v_mul_f32_e32 v34, v42, v37
	v_cmp_lt_i32_e32 vcc, 18, v134
	v_min_f32_e64 v42, -v43, s60
	v_exp_f32_e32 v42, v42
	v_cndmask_b32_e32 v43, 1.0, v34, vcc
	v_mul_f32_e32 v34, v135, v37
	v_min_f32_e64 v37, -v44, s60
	v_exp_f32_e32 v37, v37
	v_cndmask_b32_e32 v146, 0, v34, vcc
	v_add_f32_e32 v34, 1.0, v42
	v_rcp_f32_e32 v34, v34
	v_add_f32_e32 v44, 1.0, v37
	v_rcp_f32_e32 v44, v44
	v_exp_f32_e32 v45, v45
	v_min_f32_e64 v46, -v46, s60
	v_min_f32_e64 v47, -v47, s60
	v_exp_f32_e32 v46, v46
	v_exp_f32_e32 v47, v47
	v_mul_f32_e32 v42, v42, v34
	v_cmp_lt_i32_e32 vcc, 19, v134
	v_mul_f32_e32 v34, v135, v34
	v_add_f32_e32 v130, 1.0, v46
	v_cndmask_b32_e32 v147, 0, v34, vcc
	v_mul_f32_e32 v34, v37, v44
	v_add_f32_e32 v37, 1.0, v45
	v_rcp_f32_e32 v37, v37
	v_add_f32_e32 v132, 1.0, v47
	v_rcp_f32_e32 v130, v130
	v_rcp_f32_e32 v132, v132
	v_cndmask_b32_e32 v42, 1.0, v42, vcc
	v_cmp_lt_i32_e32 vcc, 24, v134
	v_mul_f32_e32 v44, v135, v44
	v_mul_f32_e32 v45, v45, v37
	v_cndmask_b32_e32 v34, 1.0, v34, vcc
	v_cndmask_b32_e32 v44, 0, v44, vcc
	v_cmp_lt_i32_e32 vcc, 25, v134
	v_mul_f32_e32 v37, v135, v37
	v_mul_f32_e32 v46, v46, v130
	v_cndmask_b32_e32 v45, 1.0, v45, vcc
	v_cndmask_b32_e32 v37, 0, v37, vcc
	v_cmp_lt_i32_e32 vcc, 26, v134
	v_mul_f32_e32 v47, v47, v132
	v_cndmask_b32_e64 v47, 1.0, v47, s[0:1]
	v_cndmask_b32_e32 v46, 1.0, v46, vcc
	v_mul_f32_e32 v34, v34, v45
	v_mul_f32_e32 v134, v46, v47
	v_mul_f32_e32 v134, v34, v134
	v_mov_b32_e32 v148, v134
	v_mov_b32_e32 v240, v134
	s_nop 1
	v_permlane32_swap_b32_e32 v148, v240
	v_cndmask_b32_e64 v148, v148, v240, s[2:3]
	v_mul_f32_e32 v34, v135, v130
	v_cndmask_b32_e32 v149, 0, v34, vcc
	v_mul_f32_e32 v34, v135, v132
	v_cndmask_b32_e64 v34, 0, v34, s[0:1]
	s_waitcnt lgkmcnt(0)
; __device__ __forceinline__ void sb_unit(const Frame& F, int b, int hd, int qi, int dry) {
;     ...
;             float run = C;
;             if (!meta && key0 + 96 < tqw + 31) SB_HALF(96);
;             if (!meta && key0 + 64 < tqw + 31 && __any(run >= SB_DEAD)) SB_HALF(64);
	v_cndmask_b32_e64 v130, 1.0, v148, s[2:3]
	v_mul_f32_e32 v135, v34, v130
	v_mul_f32_e32 v34, v36, v145
	v_mul_f32_e32 v36, v43, v42
	v_mul_f32_e32 v36, v34, v36
	v_mul_f32_e32 v32, v32, v38
	v_mul_f32_e32 v34, v142, v39
	v_mov_b32_e32 v150, v36
	v_mov_b32_e32 v240, v36
	s_nop 1
	v_permlane32_swap_b32_e32 v150, v240
	v_cndmask_b32_e64 v150, v150, v240, s[2:3]
	v_mul_f32_e32 v34, v32, v34
	v_mul_f32_e32 v47, v47, v130
	v_mov_b32_e32 v130, v34
	v_mov_b32_e32 v240, v34
	s_nop 1
	v_permlane32_swap_b32_e32 v130, v240
	v_cndmask_b32_e64 v130, v130, v240, s[2:3]
	v_mul_f32_e32 v46, v46, v47
	v_mul_f32_e32 v32, v134, v148
	s_waitcnt lgkmcnt(1)
	v_mul_f32_e32 v132, v36, v150
	v_mul_f32_e32 v45, v45, v46
	v_mul_f32_e32 v46, v37, v46
	s_waitcnt lgkmcnt(0)
	v_cndmask_b32_e64 v134, 1.0, v130, s[2:3]
	v_pk_mul_f32 v[36:37], v[32:33], v[132:133]
	v_pk_mul_f32 v[34:35], v[34:35], v[130:131]
	v_mul_f32_e32 v132, v36, v134
	v_mul_f32_e32 v134, v39, v132
	v_mul_f32_e32 v142, v142, v134
	v_mul_f32_e32 v148, v38, v142
	v_pk_mul_f32 v[38:39], v[34:35], v[36:37]
	v_mov_b32_e32 v130, v39
	v_mov_b32_e32 v240, v39
	s_nop 1
	v_permlane32_swap_b32_e32 v130, v240
	v_cndmask_b32_e64 v130, v130, v240, s[2:3]
	v_mul_f32_e32 v37, v40, v132
	v_mul_f32_e32 v40, v143, v134
	v_mul_f32_e32 v36, v141, v142
	v_mul_f32_e32 v132, v140, v148
	s_waitcnt lgkmcnt(0)
	v_cndmask_b32_e64 v34, 1.0, v130, s[2:3]
	v_mul_f32_e32 v34, v38, v34
	v_mul_f32_e32 v35, v133, v34
	v_mul_f32_e32 v33, v33, v35
	v_mul_f32_e32 v131, v131, v33
	v_mul_f32_e32 v133, v136, v34
	v_mul_f32_e32 v35, v139, v35
	v_mul_f32_e32 v33, v137, v33
	v_mul_f32_e32 v34, v138, v131
	v_cvt_pk_bf16_f32 v34, v34, v33
	v_cvt_pk_bf16_f32 v35, v35, v133
	v_cvt_pk_bf16_f32 v36, v132, v36
	v_cvt_pk_bf16_f32 v37, v40, v37
	v_cndmask_b32_e64 v33, 1.0, v150, s[2:3]
	v_mul_f32_e32 v32, v32, v33
	v_mfma_f32_32x32x16_bf16 v[0:15], v[92:95], v[34:37], v[0:15]
	v_mul_f32_e32 v33, v42, v32
	v_mul_f32_e32 v42, v43, v33
	v_mul_f32_e32 v43, v145, v42
	v_mul_f32_e32 v47, v149, v47
	v_mul_f32_e32 v40, v44, v45
	v_mul_f32_e32 v44, v147, v32
	v_mul_f32_e32 v33, v146, v33
	v_mfma_f32_32x32x16_bf16 v[16:31], v[88:91], v[34:37], v[16:31]
	v_mul_f32_e32 v32, v41, v42
	v_mul_f32_e32 v34, v144, v43
	v_cvt_pk_bf16_f32 v32, v34, v32
	v_cvt_pk_bf16_f32 v33, v33, v44
	v_cvt_pk_bf16_f32 v34, v40, v46
	v_cvt_pk_bf16_f32 v35, v47, v135
	v_mul_f32_e32 v36, v39, v130
	v_mul_f32_e32 v36, v38, v36
	v_mfma_f32_32x32x16_bf16 v[0:15], v[84:87], v[32:35], v[0:15]
	v_log_f32_e32 v36, v36
	s_nop 0
	v_add_f32_e32 v126, v126, v36
	v_mfma_f32_32x32x16_bf16 v[16:31], v[80:83], v[32:35], v[16:31]
.LBB0_364:
	s_or_b32 s0, s34, 33
	s_cmp_ge_i32 s0, s25
	s_cselect_b64 s[0:1], -1, 0
	s_or_b64 s[0:1], s[18:19], s[0:1]
	s_and_b64 vcc, exec, s[0:1]
	s_cbranch_vccnz .LBB0_367
	v_cmp_le_f32_e32 vcc, s22, v126
	s_cbranch_vccz .LBB0_367
	ds_read_b128 v[32:35], v129 offset:9216
	ds_read_b128 v[80:83], v129 offset:9248
	v_exp_f32_e32 v135, v126
	v_sub_u32_e32 v134, v124, v127
	v_cmp_lt_i32_e32 vcc, 0, v134
	s_waitcnt lgkmcnt(1)
	v_mfma_f32_32x32x16_bf16 v[32:47], v[32:35], v[48:51], 0
	v_cmp_lt_i32_e64 s[0:1], 27, v134
	s_waitcnt lgkmcnt(0)
	v_mfma_f32_32x32x16_bf16 v[32:47], v[80:83], v[52:55], v[32:47]
	ds_read_b128 v[80:83], v129 offset:9280
	ds_read_b128 v[130:133], v129 offset:9312
	s_waitcnt lgkmcnt(1)
	v_mfma_f32_32x32x16_bf16 v[32:47], v[80:83], v[56:59], v[32:47]
	ds_read_b64_tr_b16 v[92:93], v128 offset:49152
	ds_read_b64_tr_b16 v[94:95], v128 offset:50688
	ds_read_b64_tr_b16 v[90:91], v128 offset:50752
	ds_read_b64_tr_b16 v[88:89], v128 offset:49216
	ds_read_b64_tr_b16 v[84:85], v128 offset:52224
	ds_read_b64_tr_b16 v[86:87], v128 offset:53760
	ds_read_b64_tr_b16 v[82:83], v128 offset:53824
	ds_read_b64_tr_b16 v[80:81], v128 offset:52288
	s_waitcnt lgkmcnt(8)
	v_mfma_f32_32x32x16_bf16 v[32:47], v[130:133], v[60:63], v[32:47]
	s_nop 11
	v_min_f32_e64 v32, -v32, s60
	v_min_f32_e64 v33, -v33, s60
	v_exp_f32_e32 v32, v32
	v_min_f32_e64 v34, -v34, s60
	v_exp_f32_e32 v33, v33
	v_exp_f32_e32 v34, v34
	v_min_f32_e64 v35, -v35, s60
	v_exp_f32_e32 v130, v35
	v_add_f32_e32 v35, 1.0, v32
	v_add_f32_e32 v131, 1.0, v33
	v_rcp_f32_e32 v35, v35
	v_add_f32_e32 v132, 1.0, v34
	v_rcp_f32_e32 v131, v131
	v_min_f32_e64 v36, -v36, s60
	v_rcp_f32_e32 v132, v132
	v_exp_f32_e32 v36, v36
	v_add_f32_e32 v133, 1.0, v130
	v_rcp_f32_e32 v136, v133
	v_mul_f32_e32 v32, v32, v35
	v_mul_f32_e32 v133, v135, v35
	v_mul_f32_e32 v33, v33, v131
	v_mul_f32_e32 v137, v135, v131
	v_cndmask_b32_e32 v35, 1.0, v32, vcc
	v_cndmask_b32_e32 v138, 0, v133, vcc
	v_cmp_lt_i32_e32 vcc, 1, v134
	v_mul_f32_e32 v34, v34, v132
	v_mul_f32_e32 v32, v135, v132
	v_cndmask_b32_e32 v131, 1.0, v33, vcc
	v_cndmask_b32_e32 v137, 0, v137, vcc
	v_cmp_lt_i32_e32 vcc, 2, v134
	v_min_f32_e64 v39, -v39, s60
	v_cndmask_b32_e32 v33, 1.0, v34, vcc
	v_add_f32_e32 v34, 1.0, v36
	v_rcp_f32_e32 v34, v34
	v_cndmask_b32_e32 v139, 0, v32, vcc
	v_mul_f32_e32 v32, v130, v136
	v_cmp_lt_i32_e32 vcc, 3, v134
	v_exp_f32_e32 v39, v39
	v_cndmask_b32_e32 v133, 1.0, v32, vcc
	v_mul_f32_e32 v32, v135, v136
	v_cndmask_b32_e32 v136, 0, v32, vcc
	v_mul_f32_e32 v32, v36, v34
	v_min_f32_e64 v36, -v37, s60
	v_exp_f32_e32 v36, v36
	v_cmp_lt_i32_e32 vcc, 8, v134
	v_mul_f32_e32 v34, v135, v34
	v_cndmask_b32_e32 v140, 0, v34, vcc
	v_add_f32_e32 v34, 1.0, v36
	v_rcp_f32_e32 v34, v34
	v_min_f32_e64 v37, -v38, s60
	v_exp_f32_e32 v37, v37
	v_cndmask_b32_e32 v32, 1.0, v32, vcc
	v_mul_f32_e32 v36, v36, v34
	v_cmp_lt_i32_e32 vcc, 9, v134
	v_mul_f32_e32 v34, v135, v34
	v_min_f32_e64 v42, -v42, s60
	v_cndmask_b32_e32 v38, 1.0, v36, vcc
	v_add_f32_e32 v36, 1.0, v37
	v_rcp_f32_e32 v36, v36
	v_cndmask_b32_e32 v141, 0, v34, vcc
	v_cmp_lt_i32_e32 vcc, 10, v134
	v_exp_f32_e32 v42, v42
	v_mul_f32_e32 v34, v37, v36
	v_add_f32_e32 v37, 1.0, v39
	v_rcp_f32_e32 v37, v37
	v_cndmask_b32_e32 v142, 1.0, v34, vcc
	v_mul_f32_e32 v34, v135, v36
	v_cndmask_b32_e32 v143, 0, v34, vcc
	v_mul_f32_e32 v34, v39, v37
	v_cmp_lt_i32_e32 vcc, 11, v134
	v_min_f32_e64 v36, -v40, s60
	v_exp_f32_e32 v36, v36
	v_cndmask_b32_e32 v39, 1.0, v34, vcc
	v_mul_f32_e32 v34, v135, v37
	v_min_f32_e64 v37, -v41, s60
	v_exp_f32_e32 v37, v37
	v_cndmask_b32_e32 v40, 0, v34, vcc
	v_add_f32_e32 v34, 1.0, v36
	v_rcp_f32_e32 v34, v34
	v_add_f32_e32 v41, 1.0, v37
	v_rcp_f32_e32 v41, v41
	v_cmp_lt_i32_e32 vcc, 16, v134
	v_mul_f32_e32 v36, v36, v34
	v_mul_f32_e32 v34, v135, v34
	v_cndmask_b32_e32 v144, 0, v34, vcc
	v_mul_f32_e32 v34, v37, v41
	v_add_f32_e32 v37, 1.0, v42
	v_rcp_f32_e32 v37, v37
	v_cndmask_b32_e32 v36, 1.0, v36, vcc
	v_cmp_lt_i32_e32 vcc, 17, v134
	v_min_f32_e64 v45, -v45, s60
	v_cndmask_b32_e32 v145, 1.0, v34, vcc
	v_mul_f32_e32 v34, v135, v41
	v_cndmask_b32_e32 v41, 0, v34, vcc
	v_mul_f32_e32 v34, v42, v37
	v_cmp_lt_i32_e32 vcc, 18, v134
	v_min_f32_e64 v42, -v43, s60
	v_exp_f32_e32 v42, v42
	v_cndmask_b32_e32 v43, 1.0, v34, vcc
	v_mul_f32_e32 v34, v135, v37
	v_min_f32_e64 v37, -v44, s60
	v_exp_f32_e32 v37, v37
	v_cndmask_b32_e32 v146, 0, v34, vcc
	v_add_f32_e32 v34, 1.0, v42
	v_rcp_f32_e32 v34, v34
	v_add_f32_e32 v44, 1.0, v37
	v_rcp_f32_e32 v44, v44
	v_exp_f32_e32 v45, v45
	v_min_f32_e64 v46, -v46, s60
	v_min_f32_e64 v47, -v47, s60
	v_exp_f32_e32 v46, v46
	v_exp_f32_e32 v47, v47
	v_mul_f32_e32 v42, v42, v34
	v_cmp_lt_i32_e32 vcc, 19, v134
	v_mul_f32_e32 v34, v135, v34
	v_add_f32_e32 v130, 1.0, v46
	v_cndmask_b32_e32 v147, 0, v34, vcc
	v_mul_f32_e32 v34, v37, v44
	v_add_f32_e32 v37, 1.0, v45
	v_rcp_f32_e32 v37, v37
	v_add_f32_e32 v132, 1.0, v47
	v_rcp_f32_e32 v130, v130
	v_rcp_f32_e32 v132, v132
	v_cndmask_b32_e32 v42, 1.0, v42, vcc
	v_cmp_lt_i32_e32 vcc, 24, v134
	v_mul_f32_e32 v44, v135, v44
	v_mul_f32_e32 v45, v45, v37
	v_cndmask_b32_e32 v34, 1.0, v34, vcc
	v_cndmask_b32_e32 v44, 0, v44, vcc
	v_cmp_lt_i32_e32 vcc, 25, v134
	v_mul_f32_e32 v37, v135, v37
	v_mul_f32_e32 v46, v46, v130
	v_cndmask_b32_e32 v45, 1.0, v45, vcc
	v_cndmask_b32_e32 v37, 0, v37, vcc
	v_cmp_lt_i32_e32 vcc, 26, v134
	v_mul_f32_e32 v47, v47, v132
	v_cndmask_b32_e64 v47, 1.0, v47, s[0:1]
	v_cndmask_b32_e32 v46, 1.0, v46, vcc
	v_mul_f32_e32 v34, v34, v45
	v_mul_f32_e32 v134, v46, v47
	v_mul_f32_e32 v134, v34, v134
	v_mov_b32_e32 v148, v134
	v_mov_b32_e32 v240, v134
	s_nop 1
	v_permlane32_swap_b32_e32 v148, v240
	v_cndmask_b32_e64 v148, v148, v240, s[2:3]
	v_mul_f32_e32 v34, v135, v130
	v_cndmask_b32_e32 v149, 0, v34, vcc
	v_mul_f32_e32 v34, v135, v132
	v_cndmask_b32_e64 v34, 0, v34, s[0:1]
	s_waitcnt lgkmcnt(0)
	v_cndmask_b32_e64 v130, 1.0, v148, s[2:3]
	v_mul_f32_e32 v135, v34, v130
	v_mul_f32_e32 v34, v36, v145
	v_mul_f32_e32 v36, v43, v42
	v_mul_f32_e32 v36, v34, v36
	v_mul_f32_e32 v32, v32, v38
	v_mul_f32_e32 v34, v142, v39
	v_mov_b32_e32 v150, v36
	v_mov_b32_e32 v240, v36
	s_nop 1
	v_permlane32_swap_b32_e32 v150, v240
	v_cndmask_b32_e64 v150, v150, v240, s[2:3]
	v_mul_f32_e32 v34, v32, v34
	v_mul_f32_e32 v47, v47, v130
	v_mov_b32_e32 v130, v34
	v_mov_b32_e32 v240, v34
	s_nop 1
	v_permlane32_swap_b32_e32 v130, v240
	v_cndmask_b32_e64 v130, v130, v240, s[2:3]
	v_mul_f32_e32 v46, v46, v47
	v_mul_f32_e32 v32, v134, v148
	s_waitcnt lgkmcnt(1)
	v_mul_f32_e32 v132, v36, v150
	v_mul_f32_e32 v45, v45, v46
	v_mul_f32_e32 v46, v37, v46
	s_waitcnt lgkmcnt(0)
	v_cndmask_b32_e64 v134, 1.0, v130, s[2:3]
	v_pk_mul_f32 v[36:37], v[32:33], v[132:133]
	v_pk_mul_f32 v[34:35], v[34:35], v[130:131]
	v_mul_f32_e32 v132, v36, v134
	v_mul_f32_e32 v134, v39, v132
	v_mul_f32_e32 v142, v142, v134
	v_mul_f32_e32 v148, v38, v142
	v_pk_mul_f32 v[38:39], v[34:35], v[36:37]
	v_mov_b32_e32 v130, v39
	v_mov_b32_e32 v240, v39
	s_nop 1
	v_permlane32_swap_b32_e32 v130, v240
	v_cndmask_b32_e64 v130, v130, v240, s[2:3]
	v_mul_f32_e32 v37, v40, v132
	v_mul_f32_e32 v40, v143, v134
	v_mul_f32_e32 v36, v141, v142
	v_mul_f32_e32 v132, v140, v148
	s_waitcnt lgkmcnt(0)
	v_cndmask_b32_e64 v34, 1.0, v130, s[2:3]
	v_mul_f32_e32 v34, v38, v34
	v_mul_f32_e32 v35, v133, v34
	v_mul_f32_e32 v33, v33, v35
	v_mul_f32_e32 v131, v131, v33
	v_mul_f32_e32 v133, v136, v34
	v_mul_f32_e32 v35, v139, v35
	v_mul_f32_e32 v33, v137, v33
	v_mul_f32_e32 v34, v138, v131
	v_cvt_pk_bf16_f32 v34, v34, v33
	v_cvt_pk_bf16_f32 v35, v35, v133
	v_cvt_pk_bf16_f32 v36, v132, v36
	v_cvt_pk_bf16_f32 v37, v40, v37
	v_cndmask_b32_e64 v33, 1.0, v150, s[2:3]
	v_mul_f32_e32 v32, v32, v33
	v_mfma_f32_32x32x16_bf16 v[0:15], v[92:95], v[34:37], v[0:15]
	v_mul_f32_e32 v33, v42, v32
	v_mul_f32_e32 v42, v43, v33
	v_mul_f32_e32 v43, v145, v42
	v_mul_f32_e32 v47, v149, v47
	v_mul_f32_e32 v40, v44, v45
	v_mul_f32_e32 v44, v147, v32
	v_mul_f32_e32 v33, v146, v33
	v_mfma_f32_32x32x16_bf16 v[16:31], v[88:91], v[34:37], v[16:31]
	v_mul_f32_e32 v32, v41, v42
	v_mul_f32_e32 v34, v144, v43
	v_cvt_pk_bf16_f32 v32, v34, v32
	v_cvt_pk_bf16_f32 v33, v33, v44
	v_cvt_pk_bf16_f32 v34, v40, v46
	v_cvt_pk_bf16_f32 v35, v47, v135
	v_mul_f32_e32 v36, v39, v130
	v_mul_f32_e32 v36, v38, v36
	v_mfma_f32_32x32x16_bf16 v[0:15], v[84:87], v[32:35], v[0:15]
	v_log_f32_e32 v36, v36
	s_nop 0
	v_add_f32_e32 v126, v126, v36
	v_mfma_f32_32x32x16_bf16 v[16:31], v[80:83], v[32:35], v[16:31]
; __device__ __forceinline__ void sb_unit(const Frame& F, int b, int hd, int qi, int dry) {
;     ...
;             float run = C;
;             if (!meta && key0 + 96 < tqw + 31) SB_HALF(96);
;             if (!meta && key0 + 64 < tqw + 31 && __any(run >= SB_DEAD)) SB_HALF(64);
;             if (!meta && key0 + 32 < tqw + 31 && __any(run >= SB_DEAD)) SB_HALF(32);
.LBB0_367:
	s_or_b32 s0, s34, 1
	s_cmp_ge_i32 s0, s25
	s_cselect_b64 s[0:1], -1, 0
	s_or_b64 s[0:1], s[18:19], s[0:1]
	s_and_b64 vcc, exec, s[0:1]
	s_cbranch_vccnz .LBB0_370
	v_cmp_le_f32_e32 vcc, s22, v126
	s_cbranch_vccz .LBB0_370
	ds_read_b128 v[32:35], v129 offset:4608
	ds_read_b128 v[80:83], v129 offset:4640
	v_exp_f32_e32 v135, v126
	v_sub_u32_e32 v134, v125, v127
	v_cmp_lt_i32_e32 vcc, 0, v134
	s_waitcnt lgkmcnt(1)
	v_mfma_f32_32x32x16_bf16 v[32:47], v[32:35], v[48:51], 0
	v_cmp_lt_i32_e64 s[0:1], 27, v134
	s_waitcnt lgkmcnt(0)
	v_mfma_f32_32x32x16_bf16 v[32:47], v[80:83], v[52:55], v[32:47]
	ds_read_b128 v[80:83], v129 offset:4672
	ds_read_b128 v[130:133], v129 offset:4704
	s_waitcnt lgkmcnt(1)
	v_mfma_f32_32x32x16_bf16 v[32:47], v[80:83], v[56:59], v[32:47]
	ds_read_b64_tr_b16 v[92:93], v128 offset:43008
	ds_read_b64_tr_b16 v[94:95], v128 offset:44544
	ds_read_b64_tr_b16 v[90:91], v128 offset:44608
	ds_read_b64_tr_b16 v[88:89], v128 offset:43072
	ds_read_b64_tr_b16 v[84:85], v128 offset:46080
	ds_read_b64_tr_b16 v[86:87], v128 offset:47616
	ds_read_b64_tr_b16 v[82:83], v128 offset:47680
	ds_read_b64_tr_b16 v[80:81], v128 offset:46144
	s_waitcnt lgkmcnt(8)
	v_mfma_f32_32x32x16_bf16 v[32:47], v[130:133], v[60:63], v[32:47]
	s_nop 11
	v_min_f32_e64 v32, -v32, s60
	v_min_f32_e64 v33, -v33, s60
	v_exp_f32_e32 v32, v32
	v_min_f32_e64 v34, -v34, s60
	v_exp_f32_e32 v33, v33
	v_exp_f32_e32 v34, v34
	v_min_f32_e64 v35, -v35, s60
	v_exp_f32_e32 v130, v35
	v_add_f32_e32 v35, 1.0, v32
	v_add_f32_e32 v131, 1.0, v33
	v_rcp_f32_e32 v35, v35
	v_add_f32_e32 v132, 1.0, v34
	v_rcp_f32_e32 v131, v131
	v_min_f32_e64 v36, -v36, s60
	v_rcp_f32_e32 v132, v132
	v_exp_f32_e32 v36, v36
	v_add_f32_e32 v133, 1.0, v130
	v_rcp_f32_e32 v136, v133
	v_mul_f32_e32 v32, v32, v35
	v_mul_f32_e32 v133, v135, v35
	v_mul_f32_e32 v33, v33, v131
	v_mul_f32_e32 v137, v135, v131
	v_cndmask_b32_e32 v35, 1.0, v32, vcc
	v_cndmask_b32_e32 v138, 0, v133, vcc
	v_cmp_lt_i32_e32 vcc, 1, v134
	v_mul_f32_e32 v34, v34, v132
	v_mul_f32_e32 v32, v135, v132
	v_cndmask_b32_e32 v131, 1.0, v33, vcc
	v_cndmask_b32_e32 v137, 0, v137, vcc
	v_cmp_lt_i32_e32 vcc, 2, v134
	v_min_f32_e64 v39, -v39, s60
	v_cndmask_b32_e32 v33, 1.0, v34, vcc
	v_add_f32_e32 v34, 1.0, v36
	v_rcp_f32_e32 v34, v34
	v_cndmask_b32_e32 v139, 0, v32, vcc
	v_mul_f32_e32 v32, v130, v136
	v_cmp_lt_i32_e32 vcc, 3, v134
	v_exp_f32_e32 v39, v39
	v_cndmask_b32_e32 v133, 1.0, v32, vcc
	v_mul_f32_e32 v32, v135, v136
	v_cndmask_b32_e32 v136, 0, v32, vcc
	v_mul_f32_e32 v32, v36, v34
	v_min_f32_e64 v36, -v37, s60
	v_exp_f32_e32 v36, v36
	v_cmp_lt_i32_e32 vcc, 8, v134
	v_mul_f32_e32 v34, v135, v34
	v_cndmask_b32_e32 v140, 0, v34, vcc
	v_add_f32_e32 v34, 1.0, v36
	v_rcp_f32_e32 v34, v34
	v_min_f32_e64 v37, -v38, s60
	v_exp_f32_e32 v37, v37
	v_cndmask_b32_e32 v32, 1.0, v32, vcc
	v_mul_f32_e32 v36, v36, v34
	v_cmp_lt_i32_e32 vcc, 9, v134
	v_mul_f32_e32 v34, v135, v34
	v_min_f32_e64 v42, -v42, s60
	v_cndmask_b32_e32 v38, 1.0, v36, vcc
	v_add_f32_e32 v36, 1.0, v37
	v_rcp_f32_e32 v36, v36
	v_cndmask_b32_e32 v141, 0, v34, vcc
	v_cmp_lt_i32_e32 vcc, 10, v134
	v_exp_f32_e32 v42, v42
	v_mul_f32_e32 v34, v37, v36
	v_add_f32_e32 v37, 1.0, v39
	v_rcp_f32_e32 v37, v37
	v_cndmask_b32_e32 v142, 1.0, v34, vcc
	v_mul_f32_e32 v34, v135, v36
	v_cndmask_b32_e32 v143, 0, v34, vcc
	v_mul_f32_e32 v34, v39, v37
	v_cmp_lt_i32_e32 vcc, 11, v134
	v_min_f32_e64 v36, -v40, s60
	v_exp_f32_e32 v36, v36
	v_cndmask_b32_e32 v39, 1.0, v34, vcc
	v_mul_f32_e32 v34, v135, v37
	v_min_f32_e64 v37, -v41, s60
	v_exp_f32_e32 v37, v37
	v_cndmask_b32_e32 v40, 0, v34, vcc
	v_add_f32_e32 v34, 1.0, v36
	v_rcp_f32_e32 v34, v34
	v_add_f32_e32 v41, 1.0, v37
	v_rcp_f32_e32 v41, v41
	v_cmp_lt_i32_e32 vcc, 16, v134
	v_mul_f32_e32 v36, v36, v34
	v_mul_f32_e32 v34, v135, v34
	v_cndmask_b32_e32 v144, 0, v34, vcc
	v_mul_f32_e32 v34, v37, v41
	v_add_f32_e32 v37, 1.0, v42
	v_rcp_f32_e32 v37, v37
	v_cndmask_b32_e32 v36, 1.0, v36, vcc
	v_cmp_lt_i32_e32 vcc, 17, v134
	v_min_f32_e64 v45, -v45, s60
	v_cndmask_b32_e32 v145, 1.0, v34, vcc
	v_mul_f32_e32 v34, v135, v41
	v_cndmask_b32_e32 v41, 0, v34, vcc
	v_mul_f32_e32 v34, v42, v37
	v_cmp_lt_i32_e32 vcc, 18, v134
	v_min_f32_e64 v42, -v43, s60
	v_exp_f32_e32 v42, v42
	v_cndmask_b32_e32 v43, 1.0, v34, vcc
	v_mul_f32_e32 v34, v135, v37
	v_min_f32_e64 v37, -v44, s60
	v_exp_f32_e32 v37, v37
	v_cndmask_b32_e32 v146, 0, v34, vcc
	v_add_f32_e32 v34, 1.0, v42
	v_rcp_f32_e32 v34, v34
	v_add_f32_e32 v44, 1.0, v37
	v_rcp_f32_e32 v44, v44
	v_exp_f32_e32 v45, v45
	v_min_f32_e64 v46, -v46, s60
	v_min_f32_e64 v47, -v47, s60
	v_exp_f32_e32 v46, v46
	v_exp_f32_e32 v47, v47
	v_mul_f32_e32 v42, v42, v34
	v_cmp_lt_i32_e32 vcc, 19, v134
	v_mul_f32_e32 v34, v135, v34
	v_add_f32_e32 v130, 1.0, v46
	v_cndmask_b32_e32 v147, 0, v34, vcc
	v_mul_f32_e32 v34, v37, v44
	v_add_f32_e32 v37, 1.0, v45
	v_rcp_f32_e32 v37, v37
	v_add_f32_e32 v132, 1.0, v47
	v_rcp_f32_e32 v130, v130
	v_rcp_f32_e32 v132, v132
	v_cndmask_b32_e32 v42, 1.0, v42, vcc
	v_cmp_lt_i32_e32 vcc, 24, v134
	v_mul_f32_e32 v44, v135, v44
	v_mul_f32_e32 v45, v45, v37
	v_cndmask_b32_e32 v34, 1.0, v34, vcc
	v_cndmask_b32_e32 v44, 0, v44, vcc
	v_cmp_lt_i32_e32 vcc, 25, v134
	v_mul_f32_e32 v37, v135, v37
	v_mul_f32_e32 v46, v46, v130
	v_cndmask_b32_e32 v45, 1.0, v45, vcc
	v_cndmask_b32_e32 v37, 0, v37, vcc
	v_cmp_lt_i32_e32 vcc, 26, v134
	v_mul_f32_e32 v47, v47, v132
	v_cndmask_b32_e64 v47, 1.0, v47, s[0:1]
	v_cndmask_b32_e32 v46, 1.0, v46, vcc
	v_mul_f32_e32 v34, v34, v45
	v_mul_f32_e32 v134, v46, v47
	v_mul_f32_e32 v134, v34, v134
	v_mov_b32_e32 v148, v134
	v_mov_b32_e32 v240, v134
	s_nop 1
	v_permlane32_swap_b32_e32 v148, v240
	v_cndmask_b32_e64 v148, v148, v240, s[2:3]
	v_mul_f32_e32 v34, v135, v130
	v_cndmask_b32_e32 v149, 0, v34, vcc
	v_mul_f32_e32 v34, v135, v132
	v_cndmask_b32_e64 v34, 0, v34, s[0:1]
	s_waitcnt lgkmcnt(0)
; __device__ __forceinline__ void sb_unit(const Frame& F, int b, int hd, int qi, int dry) {
;     ...
;             float run = C;
;             if (!meta && key0 + 96 < tqw + 31) SB_HALF(96);
;             if (!meta && key0 + 64 < tqw + 31 && __any(run >= SB_DEAD)) SB_HALF(64);
;             if (!meta && key0 + 32 < tqw + 31 && __any(run >= SB_DEAD)) SB_HALF(32);
;             if (__any(run >= SB_DEAD)) SB_HALF(0);
	v_cndmask_b32_e64 v130, 1.0, v148, s[2:3]
	v_mul_f32_e32 v135, v34, v130
	v_mul_f32_e32 v34, v36, v145
	v_mul_f32_e32 v36, v43, v42
	v_mul_f32_e32 v36, v34, v36
	v_mul_f32_e32 v32, v32, v38
	v_mul_f32_e32 v34, v142, v39
	v_mov_b32_e32 v150, v36
	v_mov_b32_e32 v240, v36
	s_nop 1
	v_permlane32_swap_b32_e32 v150, v240
	v_cndmask_b32_e64 v150, v150, v240, s[2:3]
	v_mul_f32_e32 v34, v32, v34
	v_mul_f32_e32 v47, v47, v130
	v_mov_b32_e32 v130, v34
	v_mov_b32_e32 v240, v34
	s_nop 1
	v_permlane32_swap_b32_e32 v130, v240
	v_cndmask_b32_e64 v130, v130, v240, s[2:3]
	v_mul_f32_e32 v46, v46, v47
	v_mul_f32_e32 v32, v134, v148
	s_waitcnt lgkmcnt(1)
	v_mul_f32_e32 v132, v36, v150
	v_mul_f32_e32 v45, v45, v46
	v_mul_f32_e32 v46, v37, v46
	s_waitcnt lgkmcnt(0)
	v_cndmask_b32_e64 v134, 1.0, v130, s[2:3]
	v_pk_mul_f32 v[36:37], v[32:33], v[132:133]
	v_pk_mul_f32 v[34:35], v[34:35], v[130:131]
	v_mul_f32_e32 v132, v36, v134
	v_mul_f32_e32 v134, v39, v132
	v_mul_f32_e32 v142, v142, v134
	v_mul_f32_e32 v148, v38, v142
	v_pk_mul_f32 v[38:39], v[34:35], v[36:37]
	v_mov_b32_e32 v130, v39
	v_mov_b32_e32 v240, v39
	s_nop 1
	v_permlane32_swap_b32_e32 v130, v240
	v_cndmask_b32_e64 v130, v130, v240, s[2:3]
	v_mul_f32_e32 v37, v40, v132
	v_mul_f32_e32 v40, v143, v134
	v_mul_f32_e32 v36, v141, v142
	v_mul_f32_e32 v132, v140, v148
	s_waitcnt lgkmcnt(0)
	v_cndmask_b32_e64 v34, 1.0, v130, s[2:3]
	v_mul_f32_e32 v34, v38, v34
	v_mul_f32_e32 v35, v133, v34
	v_mul_f32_e32 v33, v33, v35
	v_mul_f32_e32 v131, v131, v33
	v_mul_f32_e32 v133, v136, v34
	v_mul_f32_e32 v35, v139, v35
	v_mul_f32_e32 v33, v137, v33
	v_mul_f32_e32 v34, v138, v131
	v_cvt_pk_bf16_f32 v34, v34, v33
	v_cvt_pk_bf16_f32 v35, v35, v133
	v_cvt_pk_bf16_f32 v36, v132, v36
	v_cvt_pk_bf16_f32 v37, v40, v37
	v_cndmask_b32_e64 v33, 1.0, v150, s[2:3]
	v_mul_f32_e32 v32, v32, v33
	v_mfma_f32_32x32x16_bf16 v[0:15], v[92:95], v[34:37], v[0:15]
	v_mul_f32_e32 v33, v42, v32
	v_mul_f32_e32 v42, v43, v33
	v_mul_f32_e32 v43, v145, v42
	v_mul_f32_e32 v47, v149, v47
	v_mul_f32_e32 v40, v44, v45
	v_mul_f32_e32 v44, v147, v32
	v_mul_f32_e32 v33, v146, v33
	v_mfma_f32_32x32x16_bf16 v[16:31], v[88:91], v[34:37], v[16:31]
	v_mul_f32_e32 v32, v41, v42
	v_mul_f32_e32 v34, v144, v43
	v_cvt_pk_bf16_f32 v32, v34, v32
	v_cvt_pk_bf16_f32 v33, v33, v44
	v_cvt_pk_bf16_f32 v34, v40, v46
	v_cvt_pk_bf16_f32 v35, v47, v135
	v_mul_f32_e32 v36, v39, v130
	v_mul_f32_e32 v36, v38, v36
	v_mfma_f32_32x32x16_bf16 v[0:15], v[84:87], v[32:35], v[0:15]
	v_log_f32_e32 v36, v36
	s_nop 0
	v_add_f32_e32 v126, v126, v36
	v_mfma_f32_32x32x16_bf16 v[16:31], v[80:83], v[32:35], v[16:31]
.LBB0_370:
	v_cmp_le_f32_e32 vcc, s22, v126
	s_cbranch_vccz .LBB0_372
	ds_read_b128 v[32:35], v129
	ds_read_b128 v[80:83], v129 offset:32
	s_waitcnt lgkmcnt(1)
	v_mfma_f32_32x32x16_bf16 v[32:47], v[32:35], v[48:51], 0
	s_waitcnt lgkmcnt(0)
	v_mfma_f32_32x32x16_bf16 v[32:47], v[80:83], v[52:55], v[32:47]
	ds_read_b128 v[80:83], v129 offset:64
	ds_read_b128 v[130:133], v129 offset:96
	v_cndmask_b32_e64 v129, v114, 16, s[18:19]
	v_sub_u32_e32 v127, v129, v127
	v_cmp_lt_i32_e32 vcc, 0, v127
	v_cmp_lt_i32_e64 s[0:1], 27, v127
	s_waitcnt lgkmcnt(1)
	v_mfma_f32_32x32x16_bf16 v[32:47], v[80:83], v[56:59], v[32:47]
	ds_read_b64_tr_b16 v[92:93], v128 offset:36864
	ds_read_b64_tr_b16 v[94:95], v128 offset:38400
	ds_read_b64_tr_b16 v[90:91], v128 offset:38464
	ds_read_b64_tr_b16 v[88:89], v128 offset:36928
	ds_read_b64_tr_b16 v[84:85], v128 offset:39936
	ds_read_b64_tr_b16 v[86:87], v128 offset:41472
	ds_read_b64_tr_b16 v[82:83], v128 offset:41536
	ds_read_b64_tr_b16 v[80:81], v128 offset:40000
	v_exp_f32_e32 v128, v126
	s_waitcnt lgkmcnt(8)
	v_mfma_f32_32x32x16_bf16 v[32:47], v[130:133], v[60:63], v[32:47]
	s_nop 11
	v_min_f32_e64 v32, -v32, s60
	v_min_f32_e64 v33, -v33, s60
	v_exp_f32_e32 v32, v32
	v_min_f32_e64 v34, -v34, s60
	v_exp_f32_e32 v33, v33
	v_exp_f32_e32 v34, v34
	v_min_f32_e64 v35, -v35, s60
	v_exp_f32_e32 v130, v35
	v_add_f32_e32 v35, 1.0, v32
	v_add_f32_e32 v129, 1.0, v33
	v_rcp_f32_e32 v35, v35
	v_add_f32_e32 v131, 1.0, v34
	v_rcp_f32_e32 v129, v129
	v_rcp_f32_e32 v131, v131
	v_add_f32_e32 v132, 1.0, v130
	v_rcp_f32_e32 v132, v132
	v_mul_f32_e32 v32, v32, v35
	v_mul_f32_e32 v133, v128, v35
	v_min_f32_e64 v36, -v36, s60
	v_mul_f32_e32 v33, v33, v129
	v_mul_f32_e32 v134, v128, v129
	v_cndmask_b32_e32 v35, 1.0, v32, vcc
	v_cndmask_b32_e32 v133, 0, v133, vcc
	v_cmp_lt_i32_e32 vcc, 1, v127
	v_mul_f32_e32 v34, v34, v131
	v_exp_f32_e32 v32, v36
	v_cndmask_b32_e32 v129, 1.0, v33, vcc
	v_cndmask_b32_e32 v134, 0, v134, vcc
	v_cmp_lt_i32_e32 vcc, 2, v127
	v_add_f32_e32 v36, 1.0, v32
	v_rcp_f32_e32 v36, v36
	v_cndmask_b32_e32 v33, 1.0, v34, vcc
	v_mul_f32_e32 v34, v128, v131
	v_cndmask_b32_e32 v135, 0, v34, vcc
	v_mul_f32_e32 v34, v130, v132
	v_cmp_lt_i32_e32 vcc, 3, v127
	v_mul_f32_e32 v32, v32, v36
	v_mul_f32_e32 v36, v128, v36
	v_cndmask_b32_e32 v131, 1.0, v34, vcc
	v_mul_f32_e32 v34, v128, v132
	v_cndmask_b32_e32 v132, 0, v34, vcc
	v_min_f32_e64 v34, -v37, s60
	v_exp_f32_e32 v34, v34
	v_cmp_lt_i32_e32 vcc, 8, v127
	v_min_f32_e64 v37, -v38, s60
	v_cndmask_b32_e32 v136, 0, v36, vcc
	v_add_f32_e32 v36, 1.0, v34
	v_rcp_f32_e32 v36, v36
	v_exp_f32_e32 v37, v37
	v_cndmask_b32_e32 v32, 1.0, v32, vcc
	v_cmp_lt_i32_e32 vcc, 9, v127
	v_mul_f32_e32 v34, v34, v36
	v_cndmask_b32_e32 v38, 1.0, v34, vcc
	v_add_f32_e32 v34, 1.0, v37
	v_min_f32_e64 v39, -v39, s60
	v_rcp_f32_e32 v34, v34
	v_exp_f32_e32 v39, v39
	v_mul_f32_e32 v36, v128, v36
	v_cndmask_b32_e32 v137, 0, v36, vcc
	v_mul_f32_e32 v36, v37, v34
	v_add_f32_e32 v37, 1.0, v39
	v_rcp_f32_e32 v37, v37
	v_cmp_lt_i32_e32 vcc, 10, v127
	v_mul_f32_e32 v34, v128, v34
	v_cndmask_b32_e32 v138, 1.0, v36, vcc
	v_cndmask_b32_e32 v139, 0, v34, vcc
	v_mul_f32_e32 v34, v39, v37
	v_cmp_lt_i32_e32 vcc, 11, v127
	v_min_f32_e64 v36, -v40, s60
	v_exp_f32_e32 v36, v36
	v_cndmask_b32_e32 v39, 1.0, v34, vcc
	v_mul_f32_e32 v34, v128, v37
	v_min_f32_e64 v37, -v41, s60
	v_exp_f32_e32 v37, v37
	v_cndmask_b32_e32 v40, 0, v34, vcc
	v_add_f32_e32 v34, 1.0, v36
	v_rcp_f32_e32 v34, v34
	v_add_f32_e32 v41, 1.0, v37
	v_min_f32_e64 v42, -v42, s60
	v_rcp_f32_e32 v41, v41
	v_exp_f32_e32 v42, v42
	v_mul_f32_e32 v36, v36, v34
	v_cmp_lt_i32_e32 vcc, 16, v127
	v_mul_f32_e32 v34, v128, v34
	v_cndmask_b32_e32 v140, 0, v34, vcc
	v_mul_f32_e32 v34, v37, v41
	v_add_f32_e32 v37, 1.0, v42
	v_rcp_f32_e32 v37, v37
	v_cndmask_b32_e32 v36, 1.0, v36, vcc
	v_cmp_lt_i32_e32 vcc, 17, v127
	v_min_f32_e64 v45, -v45, s60
	v_cndmask_b32_e32 v141, 1.0, v34, vcc
	v_mul_f32_e32 v34, v128, v41
	v_cndmask_b32_e32 v41, 0, v34, vcc
	v_mul_f32_e32 v34, v42, v37
	v_cmp_lt_i32_e32 vcc, 18, v127
	v_min_f32_e64 v42, -v43, s60
	v_exp_f32_e32 v42, v42
	v_cndmask_b32_e32 v43, 1.0, v34, vcc
	v_mul_f32_e32 v34, v128, v37
	v_min_f32_e64 v37, -v44, s60
	v_exp_f32_e32 v37, v37
	v_cndmask_b32_e32 v142, 0, v34, vcc
	v_add_f32_e32 v34, 1.0, v42
	v_rcp_f32_e32 v34, v34
	v_add_f32_e32 v44, 1.0, v37
	v_rcp_f32_e32 v44, v44
	v_exp_f32_e32 v45, v45
	v_min_f32_e64 v46, -v46, s60
	v_min_f32_e64 v47, -v47, s60
	v_exp_f32_e32 v46, v46
	v_exp_f32_e32 v47, v47
	v_mul_f32_e32 v42, v42, v34
	v_cmp_lt_i32_e32 vcc, 19, v127
	v_mul_f32_e32 v34, v128, v34
	v_add_f32_e32 v130, 1.0, v46
	v_cndmask_b32_e32 v143, 0, v34, vcc
	v_mul_f32_e32 v34, v37, v44
	v_add_f32_e32 v37, 1.0, v45
	v_rcp_f32_e32 v37, v37
	v_add_f32_e32 v144, 1.0, v47
	v_rcp_f32_e32 v130, v130
	v_rcp_f32_e32 v144, v144
	v_cndmask_b32_e32 v42, 1.0, v42, vcc
	v_cmp_lt_i32_e32 vcc, 24, v127
	v_mul_f32_e32 v44, v128, v44
	v_mul_f32_e32 v45, v45, v37
	v_cndmask_b32_e32 v34, 1.0, v34, vcc
	v_cndmask_b32_e32 v44, 0, v44, vcc
	v_cmp_lt_i32_e32 vcc, 25, v127
	v_mul_f32_e32 v37, v128, v37
	v_mul_f32_e32 v46, v46, v130
	v_cndmask_b32_e32 v45, 1.0, v45, vcc
	v_cndmask_b32_e32 v37, 0, v37, vcc
	v_cmp_lt_i32_e32 vcc, 26, v127
	v_mul_f32_e32 v47, v47, v144
	v_cndmask_b32_e64 v47, 1.0, v47, s[0:1]
	v_cndmask_b32_e32 v46, 1.0, v46, vcc
	v_mul_f32_e32 v34, v34, v45
	v_mul_f32_e32 v127, v46, v47
	v_mul_f32_e32 v127, v34, v127
	v_mov_b32_e32 v145, v127
	v_mov_b32_e32 v240, v127
	s_nop 1
	v_permlane32_swap_b32_e32 v145, v240
	v_cndmask_b32_e64 v145, v145, v240, s[2:3]
	v_mul_f32_e32 v34, v128, v130
	v_cndmask_b32_e32 v130, 0, v34, vcc
	v_mul_f32_e32 v34, v128, v144
	v_cndmask_b32_e64 v34, 0, v34, s[0:1]
	s_waitcnt lgkmcnt(0)
	v_cndmask_b32_e64 v128, 1.0, v145, s[2:3]
	v_mul_f32_e32 v144, v34, v128
	v_mul_f32_e32 v34, v36, v141
	v_mul_f32_e32 v36, v43, v42
	v_mul_f32_e32 v36, v34, v36
	v_mul_f32_e32 v32, v32, v38
	v_mul_f32_e32 v34, v138, v39
	v_mov_b32_e32 v146, v36
	v_mov_b32_e32 v240, v36
	s_nop 1
	v_permlane32_swap_b32_e32 v146, v240
	v_cndmask_b32_e64 v146, v146, v240, s[2:3]
	v_mul_f32_e32 v34, v32, v34
	v_mul_f32_e32 v47, v47, v128
	v_mov_b32_e32 v128, v34
	v_mov_b32_e32 v240, v34
	s_nop 1
	v_permlane32_swap_b32_e32 v128, v240
	v_cndmask_b32_e64 v128, v128, v240, s[2:3]
	v_mul_f32_e32 v46, v46, v47
	v_mul_f32_e32 v47, v130, v47
	v_mul_f32_e32 v32, v127, v145
	s_waitcnt lgkmcnt(1)
	v_mul_f32_e32 v130, v36, v146
	v_mul_f32_e32 v45, v45, v46
	v_mul_f32_e32 v46, v37, v46
	s_waitcnt lgkmcnt(0)
	v_cndmask_b32_e64 v127, 1.0, v128, s[2:3]
	v_pk_mul_f32 v[36:37], v[32:33], v[130:131]
	v_pk_mul_f32 v[34:35], v[34:35], v[128:129]
	v_mul_f32_e32 v127, v36, v127
	v_mul_f32_e32 v130, v39, v127
	v_mul_f32_e32 v138, v138, v130
	v_mul_f32_e32 v145, v38, v138
	v_pk_mul_f32 v[38:39], v[34:35], v[36:37]
	v_mov_b32_e32 v128, v39
	v_mov_b32_e32 v240, v39
	s_nop 1
	v_permlane32_swap_b32_e32 v128, v240
	v_cndmask_b32_e64 v128, v128, v240, s[2:3]
	v_mul_f32_e32 v37, v40, v127
	v_mul_f32_e32 v40, v139, v130
	v_mul_f32_e32 v36, v137, v138
	v_mul_f32_e32 v127, v136, v145
	s_waitcnt lgkmcnt(0)
	v_cndmask_b32_e64 v34, 1.0, v128, s[2:3]
	v_mul_f32_e32 v34, v38, v34
	v_mul_f32_e32 v35, v131, v34
	v_mul_f32_e32 v33, v33, v35
	v_mul_f32_e32 v129, v129, v33
	v_mul_f32_e32 v130, v132, v34
	v_mul_f32_e32 v35, v135, v35
	v_mul_f32_e32 v33, v134, v33
	v_mul_f32_e32 v34, v133, v129
	v_cvt_pk_bf16_f32 v34, v34, v33
	v_cvt_pk_bf16_f32 v35, v35, v130
	v_cvt_pk_bf16_f32 v36, v127, v36
	v_cvt_pk_bf16_f32 v37, v40, v37
	v_cndmask_b32_e64 v33, 1.0, v146, s[2:3]
	v_mul_f32_e32 v32, v32, v33
	v_mfma_f32_32x32x16_bf16 v[0:15], v[92:95], v[34:37], v[0:15]
	v_mul_f32_e32 v33, v42, v32
	v_mul_f32_e32 v42, v43, v33
	v_mul_f32_e32 v43, v141, v42
	v_mul_f32_e32 v40, v44, v45
	v_mul_f32_e32 v44, v143, v32
	v_mul_f32_e32 v33, v142, v33
	v_mul_f32_e32 v32, v41, v42
	v_mfma_f32_32x32x16_bf16 v[16:31], v[88:91], v[34:37], v[16:31]
	v_mul_f32_e32 v34, v140, v43
	v_cvt_pk_bf16_f32 v32, v34, v32
	v_cvt_pk_bf16_f32 v33, v33, v44
	v_cvt_pk_bf16_f32 v34, v40, v46
	v_cvt_pk_bf16_f32 v35, v47, v144
	v_mul_f32_e32 v36, v39, v128
	v_mul_f32_e32 v36, v38, v36
	v_mfma_f32_32x32x16_bf16 v[0:15], v[84:87], v[32:35], v[0:15]
	v_log_f32_e32 v36, v36
	s_nop 0
	v_add_f32_e32 v126, v126, v36
	v_mfma_f32_32x32x16_bf16 v[16:31], v[80:83], v[32:35], v[16:31]
